# conv LN reductions: xor-8/4/2/1 shuffle steps via DPP instead of ds_bpermute (second reduction block); bias routine plain stores for the mix-phase site; redundant gmlp start wait removed
# baseline (speedup 1.0000x reference)
.Lbias_col0:
	v_lshlrev_b32_e32 v162, 2, v162
	v_add_u32_e32 v163, s46, v162
	v_add_u32_e32 v164, s46, v163
	v_add_u32_e32 v165, s46, v164
	v_add_u32_e32 v166, s46, v165
	v_and_b32_e32 v160, 15, v160
	v_cmp_eq_u32_e64 s[52:53], 0, v160
	s_nop 4
	s_and_b64 exec, exec, s[52:53]
	s_cmp_eq_u32 s49, 0
	s_cbranch_scc1 .Lbias_st_plain
	global_store_dword v162, v80, s[44:45] sc1
	global_store_dword v162, v88, s[44:45] offset:4 sc1
	global_store_dword v163, v81, s[44:45] sc1
	global_store_dword v163, v89, s[44:45] offset:4 sc1
	global_store_dword v164, v82, s[44:45] sc1
	global_store_dword v164, v90, s[44:45] offset:4 sc1
	global_store_dword v165, v83, s[44:45] sc1
	global_store_dword v165, v91, s[44:45] offset:4 sc1
	global_store_dword v166, v84, s[44:45] sc1
	global_store_dword v166, v92, s[44:45] offset:4 sc1
	s_branch .Lbias_st_done
.Lbias_st_plain:
	global_store_dword v162, v80, s[44:45]
	global_store_dword v162, v88, s[44:45] offset:4
	global_store_dword v163, v81, s[44:45]
	global_store_dword v163, v89, s[44:45] offset:4
	global_store_dword v164, v82, s[44:45]
	global_store_dword v164, v90, s[44:45] offset:4
	global_store_dword v165, v83, s[44:45]
	global_store_dword v165, v91, s[44:45] offset:4
	global_store_dword v166, v84, s[44:45]
	global_store_dword v166, v92, s[44:45] offset:4
.Lbias_st_done:
	s_mov_b64 exec, s[50:51]
	s_add_i32 s54, s54, s70
	s_cmp_lt_i32 s54, s55
	s_cbranch_scc1 .Lbias_again
	v_mul_u32_u24_e32 v0, 0xc0, v228
	ds_read_b128 v[128:131], v0 offset:0
	ds_read_b128 v[132:135], v0 offset:16
	ds_read_b128 v[136:139], v0 offset:32
	ds_read_b128 v[140:143], v0 offset:48
	ds_read_b128 v[144:147], v0 offset:64
	ds_read_b128 v[148:151], v0 offset:80
	ds_read_b128 v[152:155], v0 offset:96
	ds_read_b128 v[156:159], v0 offset:112
	ds_read_b128 v[160:163], v0 offset:128
	ds_read_b128 v[164:167], v0 offset:144
	ds_read_b128 v[168:171], v0 offset:160
	ds_read_b128 v[172:175], v0 offset:176
	s_mov_b32 s28, s49
	v_readlane_b32 s40, v255, 42
	v_readlane_b32 s41, v255, 43
	v_readlane_b32 s42, v255, 44
	v_readlane_b32 s43, v255, 45
	v_readlane_b32 s44, v255, 46
	v_readlane_b32 s45, v255, 47
	v_readlane_b32 s46, v255, 48
	v_readlane_b32 s47, v255, 49
	v_readlane_b32 s48, v255, 50
	v_readlane_b32 s49, v255, 51
	v_readlane_b32 s50, v255, 52
	v_readlane_b32 s51, v255, 53
	v_readlane_b32 s52, v255, 54
	v_readlane_b32 s53, v255, 55
	v_readlane_b32 s54, v255, 56
	v_readlane_b32 s55, v255, 57
	s_waitcnt lgkmcnt(0)
	s_nop 3
	s_cmp_eq_u32 s28, 1
	s_cbranch_scc1 .Lbias_ret1
	s_cmp_eq_u32 s28, 2
	s_cbranch_scc1 .Lbias_ret2
	s_cmp_eq_u32 s28, 0
	s_cbranch_scc1 .Lbias_ret4
	s_branch .Lbias_ret3

.LBB0_521:
	s_or_b64 exec, exec, s[0:1]
	s_waitcnt lgkmcnt(0)
	s_barrier
	v_lshl_add_u32 v40, v122, 2, s69
	ds_read2st64_b32 v[10:11], v40 offset1:4
	ds_read2st64_b32 v[14:15], v40 offset0:8 offset1:12
	ds_read2st64_b32 v[20:21], v40 offset0:16 offset1:20
	ds_read2st64_b32 v[12:13], v40 offset0:112 offset1:116
	ds_read2st64_b32 v[24:25], v40 offset0:24 offset1:28
	s_waitcnt lgkmcnt(4)
	v_fma_f32 v41, v108, v10, v75
	ds_read2st64_b32 v[28:29], v40 offset0:32 offset1:36
	ds_read2st64_b32 v[32:33], v40 offset0:40 offset1:44
	ds_read2st64_b32 v[36:37], v40 offset0:48 offset1:52
	ds_read2st64_b32 v[38:39], v40 offset0:56 offset1:60
	ds_read2st64_b32 v[34:35], v40 offset0:64 offset1:68
	ds_read2st64_b32 v[30:31], v40 offset0:72 offset1:76
	ds_read2st64_b32 v[26:27], v40 offset0:80 offset1:84
	ds_read2st64_b32 v[22:23], v40 offset0:88 offset1:92
	ds_read2st64_b32 v[18:19], v40 offset0:96 offset1:100
	ds_read2st64_b32 v[16:17], v40 offset0:104 offset1:108
	ds_read2st64_b32 v[8:9], v40 offset0:120 offset1:124
	v_fma_f32 v42, v108, v11, v75
	v_fmac_f32_e32 v41, v107, v11
	ds_read2st64_b32 v[10:11], v40 offset0:128 offset1:132
	s_waitcnt lgkmcnt(14)
	v_fma_f32 v43, v108, v14, v75
	v_fmac_f32_e32 v42, v107, v14
	v_fmac_f32_e32 v41, v106, v14
	v_fma_f32 v44, v108, v15, v75
	v_fma_f32 v45, v108, v20, v75
	v_fmac_f32_e32 v43, v107, v15
	v_fmac_f32_e32 v42, v106, v15
	v_fmac_f32_e32 v41, v103, v15
	ds_read2st64_b32 v[14:15], v40 offset0:136 offset1:140
	v_fma_f32 v46, v108, v21, v75
	s_waitcnt lgkmcnt(14)
	v_fma_f32 v69, v108, v12, v75
	v_fmac_f32_e32 v44, v107, v20
	v_fmac_f32_e32 v45, v107, v21
	v_fmac_f32_e32 v43, v106, v20
	v_fmac_f32_e32 v42, v103, v20
	v_fmac_f32_e32 v41, v101, v20
	s_waitcnt lgkmcnt(13)
	v_fma_f32 v47, v108, v24, v75
	v_fma_f32 v48, v108, v25, v75
	s_waitcnt lgkmcnt(12)
	v_fma_f32 v49, v108, v28, v75
	v_fma_f32 v50, v108, v29, v75
	s_waitcnt lgkmcnt(11)
	v_fma_f32 v51, v108, v32, v75
	v_fma_f32 v52, v108, v33, v75
	s_waitcnt lgkmcnt(10)
	v_fma_f32 v53, v108, v36, v75
	v_fma_f32 v54, v108, v37, v75
	s_waitcnt lgkmcnt(9)
	v_fma_f32 v55, v108, v38, v75
	v_fma_f32 v56, v108, v39, v75
	s_waitcnt lgkmcnt(8)
	v_fma_f32 v57, v108, v34, v75
	v_fma_f32 v58, v108, v35, v75
	s_waitcnt lgkmcnt(7)
	v_fma_f32 v59, v108, v30, v75
	v_fma_f32 v60, v108, v31, v75
	s_waitcnt lgkmcnt(6)
	v_fma_f32 v61, v108, v26, v75
	v_fma_f32 v62, v108, v27, v75
	s_waitcnt lgkmcnt(5)
	v_fma_f32 v63, v108, v22, v75
	v_fma_f32 v64, v108, v23, v75
	s_waitcnt lgkmcnt(4)
	v_fma_f32 v65, v108, v18, v75
	v_fma_f32 v66, v108, v19, v75
	s_waitcnt lgkmcnt(3)
	v_fma_f32 v67, v108, v16, v75
	v_fma_f32 v68, v108, v17, v75
	v_fma_f32 v70, v108, v13, v75
	s_waitcnt lgkmcnt(2)
	v_fma_f32 v71, v108, v8, v75
	v_fmac_f32_e32 v75, v108, v9
	v_fmac_f32_e32 v46, v107, v24
	v_fmac_f32_e32 v69, v107, v13
	v_fmac_f32_e32 v44, v106, v21
	v_fmac_f32_e32 v45, v106, v24
	v_fmac_f32_e32 v43, v103, v21
	v_fmac_f32_e32 v42, v101, v21
	v_fmac_f32_e32 v41, v100, v21
	ds_read2st64_b32 v[20:21], v40 offset0:144 offset1:148
	v_fmac_f32_e32 v47, v107, v25
	v_fmac_f32_e32 v48, v107, v28
	v_fmac_f32_e32 v49, v107, v29
	v_fmac_f32_e32 v50, v107, v32
	v_fmac_f32_e32 v51, v107, v33
	v_fmac_f32_e32 v52, v107, v36
	v_fmac_f32_e32 v53, v107, v37
	v_fmac_f32_e32 v54, v107, v38
	v_fmac_f32_e32 v55, v107, v39
	v_fmac_f32_e32 v56, v107, v34
	v_fmac_f32_e32 v57, v107, v35
	v_fmac_f32_e32 v58, v107, v30
	v_fmac_f32_e32 v59, v107, v31
	v_fmac_f32_e32 v60, v107, v26
	v_fmac_f32_e32 v61, v107, v27
	v_fmac_f32_e32 v62, v107, v22
	v_fmac_f32_e32 v63, v107, v23
	v_fmac_f32_e32 v64, v107, v18
	v_fmac_f32_e32 v65, v107, v19
	v_fmac_f32_e32 v66, v107, v16
	v_fmac_f32_e32 v67, v107, v17
	v_fmac_f32_e32 v68, v107, v12
	v_fmac_f32_e32 v70, v107, v8
	v_fmac_f32_e32 v71, v107, v9
	s_waitcnt lgkmcnt(2)
	v_fmac_f32_e32 v75, v107, v10
	v_fmac_f32_e32 v46, v106, v25
	v_fmac_f32_e32 v69, v106, v8
	v_fmac_f32_e32 v44, v103, v24
	v_fmac_f32_e32 v45, v103, v25
	v_fmac_f32_e32 v43, v101, v24
	v_fmac_f32_e32 v42, v100, v24
	v_fmac_f32_e32 v41, v99, v24
	v_fmac_f32_e32 v47, v106, v28
	v_fmac_f32_e32 v48, v106, v29
	v_fmac_f32_e32 v49, v106, v32
	v_fmac_f32_e32 v50, v106, v33
	v_fmac_f32_e32 v51, v106, v36
	v_fmac_f32_e32 v52, v106, v37
	v_fmac_f32_e32 v53, v106, v38
	v_fmac_f32_e32 v54, v106, v39
	v_fmac_f32_e32 v55, v106, v34
	v_fmac_f32_e32 v56, v106, v35
	v_fmac_f32_e32 v57, v106, v30
	v_fmac_f32_e32 v58, v106, v31
	v_fmac_f32_e32 v59, v106, v26
	v_fmac_f32_e32 v60, v106, v27
	v_fmac_f32_e32 v61, v106, v22
	v_fmac_f32_e32 v62, v106, v23
	v_fmac_f32_e32 v63, v106, v18
	v_fmac_f32_e32 v64, v106, v19
	v_fmac_f32_e32 v65, v106, v16
	v_fmac_f32_e32 v66, v106, v17
	v_fmac_f32_e32 v67, v106, v12
	v_fmac_f32_e32 v68, v106, v13
	v_fmac_f32_e32 v70, v106, v9
	v_fmac_f32_e32 v71, v106, v10
	v_fmac_f32_e32 v75, v106, v11
	v_fmac_f32_e32 v46, v103, v28
	v_fmac_f32_e32 v69, v103, v9
	v_fmac_f32_e32 v44, v101, v25
	v_fmac_f32_e32 v45, v101, v28
	v_fmac_f32_e32 v43, v100, v25
	v_fmac_f32_e32 v42, v99, v25
	v_fmac_f32_e32 v41, v98, v25
	ds_read2st64_b32 v[24:25], v40 offset0:152 offset1:156
	v_fmac_f32_e32 v47, v103, v29
	v_fmac_f32_e32 v48, v103, v32
	v_fmac_f32_e32 v49, v103, v33
	v_fmac_f32_e32 v50, v103, v36
	v_fmac_f32_e32 v51, v103, v37
	v_fmac_f32_e32 v52, v103, v38
	v_fmac_f32_e32 v53, v103, v39
	v_fmac_f32_e32 v54, v103, v34
	v_fmac_f32_e32 v55, v103, v35
	v_fmac_f32_e32 v56, v103, v30
	v_fmac_f32_e32 v57, v103, v31
	v_fmac_f32_e32 v58, v103, v26
	v_fmac_f32_e32 v59, v103, v27
	v_fmac_f32_e32 v60, v103, v22
	v_fmac_f32_e32 v61, v103, v23
	v_fmac_f32_e32 v62, v103, v18
	v_fmac_f32_e32 v63, v103, v19
	v_fmac_f32_e32 v64, v103, v16
	v_fmac_f32_e32 v65, v103, v17
	v_fmac_f32_e32 v66, v103, v12
	v_fmac_f32_e32 v67, v103, v13
	v_fmac_f32_e32 v68, v103, v8
	v_fmac_f32_e32 v70, v103, v10
	v_fmac_f32_e32 v71, v103, v11
	s_waitcnt lgkmcnt(2)
	v_fmac_f32_e32 v75, v103, v14
	v_fmac_f32_e32 v46, v101, v29
	v_fmac_f32_e32 v69, v101, v10
	v_fmac_f32_e32 v44, v100, v28
	v_fmac_f32_e32 v45, v100, v29
	v_fmac_f32_e32 v43, v99, v28
	v_fmac_f32_e32 v42, v98, v28
	v_fmac_f32_e32 v41, v97, v28
	v_fmac_f32_e32 v47, v101, v32
	v_fmac_f32_e32 v48, v101, v33
	v_fmac_f32_e32 v49, v101, v36
	v_fmac_f32_e32 v50, v101, v37
	v_fmac_f32_e32 v51, v101, v38
	v_fmac_f32_e32 v52, v101, v39
	v_fmac_f32_e32 v53, v101, v34
	v_fmac_f32_e32 v54, v101, v35
	v_fmac_f32_e32 v55, v101, v30
	v_fmac_f32_e32 v56, v101, v31
	v_fmac_f32_e32 v57, v101, v26
	v_fmac_f32_e32 v58, v101, v27
	v_fmac_f32_e32 v59, v101, v22
	v_fmac_f32_e32 v60, v101, v23
	v_fmac_f32_e32 v61, v101, v18
	v_fmac_f32_e32 v62, v101, v19
	v_fmac_f32_e32 v63, v101, v16
	v_fmac_f32_e32 v64, v101, v17
	v_fmac_f32_e32 v65, v101, v12
	v_fmac_f32_e32 v66, v101, v13
	v_fmac_f32_e32 v67, v101, v8
	v_fmac_f32_e32 v68, v101, v9
	v_fmac_f32_e32 v70, v101, v11
	v_fmac_f32_e32 v71, v101, v14
	v_fmac_f32_e32 v75, v101, v15
	v_fmac_f32_e32 v46, v100, v32
	v_fmac_f32_e32 v69, v100, v11
	v_fmac_f32_e32 v44, v99, v29
	v_fmac_f32_e32 v45, v99, v32
	v_fmac_f32_e32 v43, v98, v29
	v_fmac_f32_e32 v42, v97, v29
	v_fmac_f32_e32 v41, v96, v29
	ds_read2st64_b32 v[28:29], v40 offset0:160 offset1:164
	v_fmac_f32_e32 v47, v100, v33
	v_fmac_f32_e32 v48, v100, v36
	v_fmac_f32_e32 v49, v100, v37
	v_fmac_f32_e32 v50, v100, v38
	v_fmac_f32_e32 v51, v100, v39
	v_fmac_f32_e32 v52, v100, v34
	v_fmac_f32_e32 v53, v100, v35
	v_fmac_f32_e32 v54, v100, v30
	v_fmac_f32_e32 v55, v100, v31
	v_fmac_f32_e32 v56, v100, v26
	v_fmac_f32_e32 v57, v100, v27
	v_fmac_f32_e32 v58, v100, v22
	v_fmac_f32_e32 v59, v100, v23
	v_fmac_f32_e32 v60, v100, v18
	v_fmac_f32_e32 v61, v100, v19
	v_fmac_f32_e32 v62, v100, v16
	v_fmac_f32_e32 v63, v100, v17
	v_fmac_f32_e32 v64, v100, v12
	v_fmac_f32_e32 v65, v100, v13
	v_fmac_f32_e32 v66, v100, v8
	v_fmac_f32_e32 v67, v100, v9
	v_fmac_f32_e32 v68, v100, v10
	v_fmac_f32_e32 v70, v100, v14
	v_fmac_f32_e32 v71, v100, v15
	s_waitcnt lgkmcnt(2)
	v_fmac_f32_e32 v75, v100, v20
	v_fmac_f32_e32 v46, v99, v33
	v_fmac_f32_e32 v69, v99, v14
	v_fmac_f32_e32 v44, v98, v32
	v_fmac_f32_e32 v45, v98, v33
	v_fmac_f32_e32 v43, v97, v32
	v_fmac_f32_e32 v42, v96, v32
	v_fmac_f32_e32 v41, v95, v32
	v_fmac_f32_e32 v47, v99, v36
	v_fmac_f32_e32 v48, v99, v37
	v_fmac_f32_e32 v49, v99, v38
	v_fmac_f32_e32 v50, v99, v39
	v_fmac_f32_e32 v51, v99, v34
	v_fmac_f32_e32 v52, v99, v35
	v_fmac_f32_e32 v53, v99, v30
	v_fmac_f32_e32 v54, v99, v31
	v_fmac_f32_e32 v55, v99, v26
	v_fmac_f32_e32 v56, v99, v27
	v_fmac_f32_e32 v57, v99, v22
	v_fmac_f32_e32 v58, v99, v23
	v_fmac_f32_e32 v59, v99, v18
	v_fmac_f32_e32 v60, v99, v19
	v_fmac_f32_e32 v61, v99, v16
	v_fmac_f32_e32 v62, v99, v17
	v_fmac_f32_e32 v63, v99, v12
	v_fmac_f32_e32 v64, v99, v13
	v_fmac_f32_e32 v65, v99, v8
	v_fmac_f32_e32 v66, v99, v9
	v_fmac_f32_e32 v67, v99, v10
	v_fmac_f32_e32 v68, v99, v11
	v_fmac_f32_e32 v70, v99, v15
	v_fmac_f32_e32 v71, v99, v20
	v_fmac_f32_e32 v75, v99, v21
	v_fmac_f32_e32 v46, v98, v36
	v_fmac_f32_e32 v69, v98, v15
	v_fmac_f32_e32 v44, v97, v33
	v_fmac_f32_e32 v45, v97, v36
	v_fmac_f32_e32 v43, v96, v33
	v_fmac_f32_e32 v42, v95, v33
	v_fmac_f32_e32 v41, v94, v33
	ds_read2st64_b32 v[32:33], v40 offset0:168 offset1:172
	v_fmac_f32_e32 v47, v98, v37
	v_fmac_f32_e32 v48, v98, v38
	v_fmac_f32_e32 v49, v98, v39
	v_fmac_f32_e32 v50, v98, v34
	v_fmac_f32_e32 v51, v98, v35
	v_fmac_f32_e32 v52, v98, v30
	v_fmac_f32_e32 v53, v98, v31
	v_fmac_f32_e32 v54, v98, v26
	v_fmac_f32_e32 v55, v98, v27
	v_fmac_f32_e32 v56, v98, v22
	v_fmac_f32_e32 v57, v98, v23
	v_fmac_f32_e32 v58, v98, v18
	v_fmac_f32_e32 v59, v98, v19
	v_fmac_f32_e32 v60, v98, v16
	v_fmac_f32_e32 v61, v98, v17
	v_fmac_f32_e32 v62, v98, v12
	v_fmac_f32_e32 v63, v98, v13
	v_fmac_f32_e32 v64, v98, v8
	v_fmac_f32_e32 v65, v98, v9
	v_fmac_f32_e32 v66, v98, v10
	v_fmac_f32_e32 v67, v98, v11
	v_fmac_f32_e32 v68, v98, v14
	v_fmac_f32_e32 v70, v98, v20
	v_fmac_f32_e32 v71, v98, v21
	s_waitcnt lgkmcnt(2)
	v_fmac_f32_e32 v75, v98, v24
	v_fmac_f32_e32 v46, v97, v37
	v_fmac_f32_e32 v69, v97, v20
	v_fmac_f32_e32 v44, v96, v36
	v_fmac_f32_e32 v45, v96, v37
	v_fmac_f32_e32 v43, v95, v36
	v_fmac_f32_e32 v42, v94, v36
	v_fmac_f32_e32 v41, v93, v36
	v_fmac_f32_e32 v47, v97, v38
	v_fmac_f32_e32 v48, v97, v39
	v_fmac_f32_e32 v49, v97, v34
	v_fmac_f32_e32 v50, v97, v35
	v_fmac_f32_e32 v51, v97, v30
	v_fmac_f32_e32 v52, v97, v31
	v_fmac_f32_e32 v53, v97, v26
	v_fmac_f32_e32 v54, v97, v27
	v_fmac_f32_e32 v55, v97, v22
	v_fmac_f32_e32 v56, v97, v23
	v_fmac_f32_e32 v57, v97, v18
	v_fmac_f32_e32 v58, v97, v19
	v_fmac_f32_e32 v59, v97, v16
	v_fmac_f32_e32 v60, v97, v17
	v_fmac_f32_e32 v61, v97, v12
	v_fmac_f32_e32 v62, v97, v13
	v_fmac_f32_e32 v63, v97, v8
	v_fmac_f32_e32 v64, v97, v9
	v_fmac_f32_e32 v65, v97, v10
	v_fmac_f32_e32 v66, v97, v11
	v_fmac_f32_e32 v67, v97, v14
	v_fmac_f32_e32 v68, v97, v15
	v_fmac_f32_e32 v70, v97, v21
	v_fmac_f32_e32 v71, v97, v24
	v_fmac_f32_e32 v75, v97, v25
	v_fmac_f32_e32 v46, v96, v38
	v_fmac_f32_e32 v69, v96, v21
	v_fmac_f32_e32 v44, v95, v37
	v_fmac_f32_e32 v45, v95, v38
	v_fmac_f32_e32 v43, v94, v37
	v_fmac_f32_e32 v42, v93, v37
	v_fmac_f32_e32 v41, v92, v37
	ds_read2st64_b32 v[36:37], v40 offset0:176 offset1:180
	v_fmac_f32_e32 v47, v96, v39
	v_fmac_f32_e32 v48, v96, v34
	v_fmac_f32_e32 v49, v96, v35
	v_fmac_f32_e32 v50, v96, v30
	v_fmac_f32_e32 v51, v96, v31
	v_fmac_f32_e32 v52, v96, v26
	v_fmac_f32_e32 v53, v96, v27
	v_fmac_f32_e32 v54, v96, v22
	v_fmac_f32_e32 v55, v96, v23
	v_fmac_f32_e32 v56, v96, v18
	v_fmac_f32_e32 v57, v96, v19
	v_fmac_f32_e32 v58, v96, v16
	v_fmac_f32_e32 v59, v96, v17
	v_fmac_f32_e32 v60, v96, v12
	v_fmac_f32_e32 v61, v96, v13
	v_fmac_f32_e32 v62, v96, v8
	v_fmac_f32_e32 v63, v96, v9
	v_fmac_f32_e32 v64, v96, v10
	v_fmac_f32_e32 v65, v96, v11
	v_fmac_f32_e32 v66, v96, v14
	v_fmac_f32_e32 v67, v96, v15
	v_fmac_f32_e32 v68, v96, v20
	v_fmac_f32_e32 v70, v96, v24
	v_fmac_f32_e32 v71, v96, v25
	s_waitcnt lgkmcnt(2)
	v_fmac_f32_e32 v75, v96, v28
	v_fmac_f32_e32 v46, v95, v39
	v_fmac_f32_e32 v69, v95, v24
	v_fmac_f32_e32 v44, v94, v38
	v_fmac_f32_e32 v45, v94, v39
	v_fmac_f32_e32 v43, v93, v38
	v_fmac_f32_e32 v42, v92, v38
	v_fmac_f32_e32 v41, v91, v38
	v_fmac_f32_e32 v47, v95, v34
	v_fmac_f32_e32 v48, v95, v35
	v_fmac_f32_e32 v49, v95, v30
	v_fmac_f32_e32 v50, v95, v31
	v_fmac_f32_e32 v51, v95, v26
	v_fmac_f32_e32 v52, v95, v27
	v_fmac_f32_e32 v53, v95, v22
	v_fmac_f32_e32 v54, v95, v23
	v_fmac_f32_e32 v55, v95, v18
	v_fmac_f32_e32 v56, v95, v19
	v_fmac_f32_e32 v57, v95, v16
	v_fmac_f32_e32 v58, v95, v17
	v_fmac_f32_e32 v59, v95, v12
	v_fmac_f32_e32 v60, v95, v13
	v_fmac_f32_e32 v61, v95, v8
	v_fmac_f32_e32 v62, v95, v9
	v_fmac_f32_e32 v63, v95, v10
	v_fmac_f32_e32 v64, v95, v11
	v_fmac_f32_e32 v65, v95, v14
	v_fmac_f32_e32 v66, v95, v15
	v_fmac_f32_e32 v67, v95, v20
	v_fmac_f32_e32 v68, v95, v21
	v_fmac_f32_e32 v70, v95, v25
	v_fmac_f32_e32 v71, v95, v28
	v_fmac_f32_e32 v75, v95, v29
	v_fmac_f32_e32 v46, v94, v34
	v_fmac_f32_e32 v69, v94, v25
	v_fmac_f32_e32 v44, v93, v39
	v_fmac_f32_e32 v45, v93, v34
	v_fmac_f32_e32 v43, v92, v39
	v_fmac_f32_e32 v42, v91, v39
	v_fmac_f32_e32 v41, v90, v39
	ds_read2st64_b32 v[38:39], v40 offset0:184 offset1:188
	v_fmac_f32_e32 v47, v94, v35
	v_fmac_f32_e32 v48, v94, v30
	v_fmac_f32_e32 v49, v94, v31
	v_fmac_f32_e32 v50, v94, v26
	v_fmac_f32_e32 v51, v94, v27
	v_fmac_f32_e32 v52, v94, v22
	v_fmac_f32_e32 v53, v94, v23
	v_fmac_f32_e32 v54, v94, v18
	v_fmac_f32_e32 v55, v94, v19
	v_fmac_f32_e32 v56, v94, v16
	v_fmac_f32_e32 v57, v94, v17
	v_fmac_f32_e32 v58, v94, v12
	v_fmac_f32_e32 v59, v94, v13
	v_fmac_f32_e32 v60, v94, v8
	v_fmac_f32_e32 v61, v94, v9
	v_fmac_f32_e32 v62, v94, v10
	v_fmac_f32_e32 v63, v94, v11
	v_fmac_f32_e32 v64, v94, v14
	v_fmac_f32_e32 v65, v94, v15
	v_fmac_f32_e32 v66, v94, v20
	v_fmac_f32_e32 v67, v94, v21
	v_fmac_f32_e32 v68, v94, v24
	v_fmac_f32_e32 v70, v94, v28
	v_fmac_f32_e32 v71, v94, v29
	s_waitcnt lgkmcnt(2)
	v_fmac_f32_e32 v75, v94, v32
	v_fmac_f32_e32 v46, v93, v35
	v_fmac_f32_e32 v69, v93, v28
	v_fmac_f32_e32 v44, v92, v34
	v_fmac_f32_e32 v45, v92, v35
	v_fmac_f32_e32 v43, v91, v34
	v_fmac_f32_e32 v42, v90, v34
	v_fmac_f32_e32 v41, v89, v34
	v_fmac_f32_e32 v47, v93, v30
	v_fmac_f32_e32 v48, v93, v31
	v_fmac_f32_e32 v49, v93, v26
	v_fmac_f32_e32 v50, v93, v27
	v_fmac_f32_e32 v51, v93, v22
	v_fmac_f32_e32 v52, v93, v23
	v_fmac_f32_e32 v53, v93, v18
	v_fmac_f32_e32 v54, v93, v19
	v_fmac_f32_e32 v55, v93, v16
	v_fmac_f32_e32 v56, v93, v17
	v_fmac_f32_e32 v57, v93, v12
	v_fmac_f32_e32 v58, v93, v13
	v_fmac_f32_e32 v59, v93, v8
	v_fmac_f32_e32 v60, v93, v9
	v_fmac_f32_e32 v61, v93, v10
	v_fmac_f32_e32 v62, v93, v11
	v_fmac_f32_e32 v63, v93, v14
	v_fmac_f32_e32 v64, v93, v15
	v_fmac_f32_e32 v65, v93, v20
	v_fmac_f32_e32 v66, v93, v21
	v_fmac_f32_e32 v67, v93, v24
	v_fmac_f32_e32 v68, v93, v25
	v_fmac_f32_e32 v70, v93, v29
	v_fmac_f32_e32 v71, v93, v32
	v_fmac_f32_e32 v75, v93, v33
	v_fmac_f32_e32 v46, v92, v30
	v_fmac_f32_e32 v69, v92, v29
	v_fmac_f32_e32 v44, v91, v35
	v_fmac_f32_e32 v45, v91, v30
	v_fmac_f32_e32 v43, v90, v35
	v_fmac_f32_e32 v42, v89, v35
	v_fmac_f32_e32 v41, v88, v35
	ds_read2st64_b32 v[34:35], v40 offset0:192 offset1:196
	v_fmac_f32_e32 v47, v92, v31
	v_fmac_f32_e32 v48, v92, v26
	v_fmac_f32_e32 v49, v92, v27
	v_fmac_f32_e32 v50, v92, v22
	v_fmac_f32_e32 v51, v92, v23
	v_fmac_f32_e32 v52, v92, v18
	v_fmac_f32_e32 v53, v92, v19
	v_fmac_f32_e32 v54, v92, v16
	v_fmac_f32_e32 v55, v92, v17
	v_fmac_f32_e32 v56, v92, v12
	v_fmac_f32_e32 v57, v92, v13
	v_fmac_f32_e32 v58, v92, v8
	v_fmac_f32_e32 v59, v92, v9
	v_fmac_f32_e32 v60, v92, v10
	v_fmac_f32_e32 v61, v92, v11
	v_fmac_f32_e32 v62, v92, v14
	v_fmac_f32_e32 v63, v92, v15
	v_fmac_f32_e32 v64, v92, v20
	v_fmac_f32_e32 v65, v92, v21
	v_fmac_f32_e32 v66, v92, v24
	v_fmac_f32_e32 v67, v92, v25
	v_fmac_f32_e32 v68, v92, v28
	v_fmac_f32_e32 v70, v92, v32
	v_fmac_f32_e32 v71, v92, v33
	s_waitcnt lgkmcnt(2)
	v_fmac_f32_e32 v75, v92, v36
	v_fmac_f32_e32 v46, v91, v31
	v_fmac_f32_e32 v69, v91, v32
	v_fmac_f32_e32 v44, v90, v30
	v_fmac_f32_e32 v45, v90, v31
	v_fmac_f32_e32 v43, v89, v30
	v_fmac_f32_e32 v42, v88, v30
	v_fmac_f32_e32 v41, v87, v30
	v_fmac_f32_e32 v47, v91, v26
	v_fmac_f32_e32 v48, v91, v27
	v_fmac_f32_e32 v49, v91, v22
	v_fmac_f32_e32 v50, v91, v23
	v_fmac_f32_e32 v51, v91, v18
	v_fmac_f32_e32 v52, v91, v19
	v_fmac_f32_e32 v53, v91, v16
	v_fmac_f32_e32 v54, v91, v17
	v_fmac_f32_e32 v55, v91, v12
	v_fmac_f32_e32 v56, v91, v13
	v_fmac_f32_e32 v57, v91, v8
	v_fmac_f32_e32 v58, v91, v9
	v_fmac_f32_e32 v59, v91, v10
	v_fmac_f32_e32 v60, v91, v11
	v_fmac_f32_e32 v61, v91, v14
	v_fmac_f32_e32 v62, v91, v15
	v_fmac_f32_e32 v63, v91, v20
	v_fmac_f32_e32 v64, v91, v21
	v_fmac_f32_e32 v65, v91, v24
	v_fmac_f32_e32 v66, v91, v25
	v_fmac_f32_e32 v67, v91, v28
	v_fmac_f32_e32 v68, v91, v29
	v_fmac_f32_e32 v70, v91, v33
	v_fmac_f32_e32 v71, v91, v36
	v_fmac_f32_e32 v75, v91, v37
	v_fmac_f32_e32 v46, v90, v26
	v_fmac_f32_e32 v69, v90, v33
	v_fmac_f32_e32 v44, v89, v31
	v_fmac_f32_e32 v45, v89, v26
	v_fmac_f32_e32 v43, v88, v31
	v_fmac_f32_e32 v42, v87, v31
	v_fmac_f32_e32 v41, v86, v31
	ds_read2st64_b32 v[30:31], v40 offset0:200 offset1:204
	v_fmac_f32_e32 v47, v90, v27
	v_fmac_f32_e32 v48, v90, v22
	v_fmac_f32_e32 v49, v90, v23
	v_fmac_f32_e32 v50, v90, v18
	v_fmac_f32_e32 v51, v90, v19
	v_fmac_f32_e32 v52, v90, v16
	v_fmac_f32_e32 v53, v90, v17
	v_fmac_f32_e32 v54, v90, v12
	v_fmac_f32_e32 v55, v90, v13
	v_fmac_f32_e32 v56, v90, v8
	v_fmac_f32_e32 v57, v90, v9
	v_fmac_f32_e32 v58, v90, v10
	v_fmac_f32_e32 v59, v90, v11
	v_fmac_f32_e32 v60, v90, v14
	v_fmac_f32_e32 v61, v90, v15
	v_fmac_f32_e32 v62, v90, v20
	v_fmac_f32_e32 v63, v90, v21
	v_fmac_f32_e32 v64, v90, v24
	v_fmac_f32_e32 v65, v90, v25
	v_fmac_f32_e32 v66, v90, v28
	v_fmac_f32_e32 v67, v90, v29
	v_fmac_f32_e32 v68, v90, v32
	v_fmac_f32_e32 v70, v90, v36
	v_fmac_f32_e32 v71, v90, v37
	s_waitcnt lgkmcnt(2)
	v_fmac_f32_e32 v75, v90, v38
	v_fmac_f32_e32 v46, v89, v27
	v_fmac_f32_e32 v69, v89, v36
	v_fmac_f32_e32 v44, v88, v26
	v_fmac_f32_e32 v45, v88, v27
	v_fmac_f32_e32 v43, v87, v26
	v_fmac_f32_e32 v42, v86, v26
	v_fmac_f32_e32 v41, v85, v26
	v_fmac_f32_e32 v47, v89, v22
	v_fmac_f32_e32 v48, v89, v23
	v_fmac_f32_e32 v49, v89, v18
	v_fmac_f32_e32 v50, v89, v19
	v_fmac_f32_e32 v51, v89, v16
	v_fmac_f32_e32 v52, v89, v17
	v_fmac_f32_e32 v53, v89, v12
	v_fmac_f32_e32 v54, v89, v13
	v_fmac_f32_e32 v55, v89, v8
	v_fmac_f32_e32 v56, v89, v9
	v_fmac_f32_e32 v57, v89, v10
	v_fmac_f32_e32 v58, v89, v11
	v_fmac_f32_e32 v59, v89, v14
	v_fmac_f32_e32 v60, v89, v15
	v_fmac_f32_e32 v61, v89, v20
	v_fmac_f32_e32 v62, v89, v21
	v_fmac_f32_e32 v63, v89, v24
	v_fmac_f32_e32 v64, v89, v25
	v_fmac_f32_e32 v65, v89, v28
	v_fmac_f32_e32 v66, v89, v29
	v_fmac_f32_e32 v67, v89, v32
	v_fmac_f32_e32 v68, v89, v33
	v_fmac_f32_e32 v70, v89, v37
	v_fmac_f32_e32 v71, v89, v38
	v_fmac_f32_e32 v75, v89, v39
	v_fmac_f32_e32 v46, v88, v22
	v_fmac_f32_e32 v69, v88, v37
	v_fmac_f32_e32 v44, v87, v27
	v_fmac_f32_e32 v45, v87, v22
	v_fmac_f32_e32 v43, v86, v27
	v_fmac_f32_e32 v42, v85, v27
	v_fmac_f32_e32 v41, v84, v27
	ds_read2st64_b32 v[26:27], v40 offset0:208 offset1:212
	v_fmac_f32_e32 v47, v88, v23
	v_fmac_f32_e32 v48, v88, v18
	v_fmac_f32_e32 v49, v88, v19
	v_fmac_f32_e32 v50, v88, v16
	v_fmac_f32_e32 v51, v88, v17
	v_fmac_f32_e32 v52, v88, v12
	v_fmac_f32_e32 v53, v88, v13
	v_fmac_f32_e32 v54, v88, v8
	v_fmac_f32_e32 v55, v88, v9
	v_fmac_f32_e32 v56, v88, v10
	v_fmac_f32_e32 v57, v88, v11
	v_fmac_f32_e32 v58, v88, v14
	v_fmac_f32_e32 v59, v88, v15
	v_fmac_f32_e32 v60, v88, v20
	v_fmac_f32_e32 v61, v88, v21
	v_fmac_f32_e32 v62, v88, v24
	v_fmac_f32_e32 v63, v88, v25
	v_fmac_f32_e32 v64, v88, v28
	v_fmac_f32_e32 v65, v88, v29
	v_fmac_f32_e32 v66, v88, v32
	v_fmac_f32_e32 v67, v88, v33
	v_fmac_f32_e32 v68, v88, v36
	v_fmac_f32_e32 v70, v88, v38
	v_fmac_f32_e32 v71, v88, v39
	s_waitcnt lgkmcnt(2)
	v_fmac_f32_e32 v75, v88, v34
	v_fmac_f32_e32 v46, v87, v23
	v_fmac_f32_e32 v69, v87, v38
	v_fmac_f32_e32 v44, v86, v22
	v_fmac_f32_e32 v45, v86, v23
	v_fmac_f32_e32 v43, v85, v22
	v_fmac_f32_e32 v42, v84, v22
	v_fmac_f32_e32 v41, v83, v22
	v_fmac_f32_e32 v47, v87, v18
	v_fmac_f32_e32 v48, v87, v19
	v_fmac_f32_e32 v49, v87, v16
	v_fmac_f32_e32 v50, v87, v17
	v_fmac_f32_e32 v51, v87, v12
	v_fmac_f32_e32 v52, v87, v13
	v_fmac_f32_e32 v53, v87, v8
	v_fmac_f32_e32 v54, v87, v9
	v_fmac_f32_e32 v55, v87, v10
	v_fmac_f32_e32 v56, v87, v11
	v_fmac_f32_e32 v57, v87, v14
	v_fmac_f32_e32 v58, v87, v15
	v_fmac_f32_e32 v59, v87, v20
	v_fmac_f32_e32 v60, v87, v21
	v_fmac_f32_e32 v61, v87, v24
	v_fmac_f32_e32 v62, v87, v25
	v_fmac_f32_e32 v63, v87, v28
	v_fmac_f32_e32 v64, v87, v29
	v_fmac_f32_e32 v65, v87, v32
	v_fmac_f32_e32 v66, v87, v33
	v_fmac_f32_e32 v67, v87, v36
	v_fmac_f32_e32 v68, v87, v37
	v_fmac_f32_e32 v70, v87, v39
	v_fmac_f32_e32 v71, v87, v34
	v_fmac_f32_e32 v75, v87, v35
	v_fmac_f32_e32 v46, v86, v18
	v_fmac_f32_e32 v69, v86, v39
	v_fmac_f32_e32 v44, v85, v23
	v_fmac_f32_e32 v45, v85, v18
	v_fmac_f32_e32 v43, v84, v23
	v_fmac_f32_e32 v42, v83, v23
	v_fmac_f32_e32 v41, v82, v23
	ds_read2st64_b32 v[22:23], v40 offset0:216 offset1:220
	v_fmac_f32_e32 v47, v86, v19
	v_fmac_f32_e32 v48, v86, v16
	v_fmac_f32_e32 v49, v86, v17
	v_fmac_f32_e32 v50, v86, v12
	v_fmac_f32_e32 v51, v86, v13
	v_fmac_f32_e32 v52, v86, v8
	v_fmac_f32_e32 v53, v86, v9
	v_fmac_f32_e32 v54, v86, v10
	v_fmac_f32_e32 v55, v86, v11
	v_fmac_f32_e32 v56, v86, v14
	v_fmac_f32_e32 v57, v86, v15
	v_fmac_f32_e32 v58, v86, v20
	v_fmac_f32_e32 v59, v86, v21
	v_fmac_f32_e32 v60, v86, v24
	v_fmac_f32_e32 v61, v86, v25
	v_fmac_f32_e32 v62, v86, v28
	v_fmac_f32_e32 v63, v86, v29
	v_fmac_f32_e32 v64, v86, v32
	v_fmac_f32_e32 v65, v86, v33
	v_fmac_f32_e32 v66, v86, v36
	v_fmac_f32_e32 v67, v86, v37
	v_fmac_f32_e32 v68, v86, v38
	v_fmac_f32_e32 v70, v86, v34
	v_fmac_f32_e32 v71, v86, v35
	s_waitcnt lgkmcnt(2)
	v_fmac_f32_e32 v75, v86, v30
	v_fmac_f32_e32 v46, v85, v19
	v_fmac_f32_e32 v69, v85, v34
	v_fmac_f32_e32 v44, v84, v18
	v_fmac_f32_e32 v45, v84, v19
	v_fmac_f32_e32 v43, v83, v18
	v_fmac_f32_e32 v42, v82, v18
	v_fmac_f32_e32 v41, v81, v18
	v_fmac_f32_e32 v47, v85, v16
	v_fmac_f32_e32 v48, v85, v17
	v_fmac_f32_e32 v49, v85, v12
	v_fmac_f32_e32 v50, v85, v13
	v_fmac_f32_e32 v51, v85, v8
	v_fmac_f32_e32 v52, v85, v9
	v_fmac_f32_e32 v53, v85, v10
	v_fmac_f32_e32 v54, v85, v11
	v_fmac_f32_e32 v55, v85, v14
	v_fmac_f32_e32 v56, v85, v15
	v_fmac_f32_e32 v57, v85, v20
	v_fmac_f32_e32 v58, v85, v21
	v_fmac_f32_e32 v59, v85, v24
	v_fmac_f32_e32 v60, v85, v25
	v_fmac_f32_e32 v61, v85, v28
	v_fmac_f32_e32 v62, v85, v29
	v_fmac_f32_e32 v63, v85, v32
	v_fmac_f32_e32 v64, v85, v33
	v_fmac_f32_e32 v65, v85, v36
	v_fmac_f32_e32 v66, v85, v37
	v_fmac_f32_e32 v67, v85, v38
	v_fmac_f32_e32 v68, v85, v39
	v_fmac_f32_e32 v70, v85, v35
	v_fmac_f32_e32 v71, v85, v30
	v_fmac_f32_e32 v75, v85, v31
	v_fmac_f32_e32 v46, v84, v16
	v_fmac_f32_e32 v69, v84, v35
	v_fmac_f32_e32 v44, v83, v19
	v_fmac_f32_e32 v45, v83, v16
	v_fmac_f32_e32 v43, v82, v19
	v_fmac_f32_e32 v42, v81, v19
	v_fmac_f32_e32 v41, v80, v19
	ds_read2st64_b32 v[18:19], v40 offset0:224 offset1:228
	v_fmac_f32_e32 v47, v84, v17
	v_fmac_f32_e32 v48, v84, v12
	v_fmac_f32_e32 v49, v84, v13
	v_fmac_f32_e32 v50, v84, v8
	v_fmac_f32_e32 v51, v84, v9
	v_fmac_f32_e32 v52, v84, v10
	v_fmac_f32_e32 v53, v84, v11
	v_fmac_f32_e32 v54, v84, v14
	v_fmac_f32_e32 v55, v84, v15
	v_fmac_f32_e32 v56, v84, v20
	v_fmac_f32_e32 v57, v84, v21
	v_fmac_f32_e32 v58, v84, v24
	v_fmac_f32_e32 v59, v84, v25
	v_fmac_f32_e32 v60, v84, v28
	v_fmac_f32_e32 v61, v84, v29
	v_fmac_f32_e32 v62, v84, v32
	v_fmac_f32_e32 v63, v84, v33
	v_fmac_f32_e32 v64, v84, v36
	v_fmac_f32_e32 v65, v84, v37
	v_fmac_f32_e32 v66, v84, v38
	v_fmac_f32_e32 v67, v84, v39
	v_fmac_f32_e32 v68, v84, v34
	v_fmac_f32_e32 v70, v84, v30
	v_fmac_f32_e32 v71, v84, v31
	s_waitcnt lgkmcnt(2)
	v_fmac_f32_e32 v75, v84, v26
	v_fmac_f32_e32 v46, v83, v17
	v_fmac_f32_e32 v69, v83, v30
	v_fmac_f32_e32 v44, v82, v16
	v_fmac_f32_e32 v45, v82, v17
	v_fmac_f32_e32 v43, v81, v16
	v_fmac_f32_e32 v42, v80, v16
	v_fmac_f32_e32 v41, v79, v16
	v_fmac_f32_e32 v47, v83, v12
	v_fmac_f32_e32 v48, v83, v13
	v_fmac_f32_e32 v49, v83, v8
	v_fmac_f32_e32 v50, v83, v9
	v_fmac_f32_e32 v51, v83, v10
	v_fmac_f32_e32 v52, v83, v11
	v_fmac_f32_e32 v53, v83, v14
	v_fmac_f32_e32 v54, v83, v15
	v_fmac_f32_e32 v55, v83, v20
	v_fmac_f32_e32 v56, v83, v21
	v_fmac_f32_e32 v57, v83, v24
	v_fmac_f32_e32 v58, v83, v25
	v_fmac_f32_e32 v59, v83, v28
	v_fmac_f32_e32 v60, v83, v29
	v_fmac_f32_e32 v61, v83, v32
	v_fmac_f32_e32 v62, v83, v33
	v_fmac_f32_e32 v63, v83, v36
	v_fmac_f32_e32 v64, v83, v37
	v_fmac_f32_e32 v65, v83, v38
	v_fmac_f32_e32 v66, v83, v39
	v_fmac_f32_e32 v67, v83, v34
	v_fmac_f32_e32 v68, v83, v35
	v_fmac_f32_e32 v70, v83, v31
	v_fmac_f32_e32 v71, v83, v26
	v_fmac_f32_e32 v75, v83, v27
	v_fmac_f32_e32 v46, v82, v12
	v_fmac_f32_e32 v69, v82, v31
	v_fmac_f32_e32 v44, v81, v17
	v_fmac_f32_e32 v45, v81, v12
	v_fmac_f32_e32 v43, v80, v17
	v_fmac_f32_e32 v42, v79, v17
	v_fmac_f32_e32 v41, v78, v17
	ds_read2st64_b32 v[16:17], v40 offset0:232 offset1:236
	v_fmac_f32_e32 v47, v82, v13
	v_fmac_f32_e32 v48, v82, v8
	v_fmac_f32_e32 v49, v82, v9
	v_fmac_f32_e32 v50, v82, v10
	v_fmac_f32_e32 v51, v82, v11
	v_fmac_f32_e32 v52, v82, v14
	v_fmac_f32_e32 v53, v82, v15
	v_fmac_f32_e32 v54, v82, v20
	v_fmac_f32_e32 v55, v82, v21
	v_fmac_f32_e32 v56, v82, v24
	v_fmac_f32_e32 v57, v82, v25
	v_fmac_f32_e32 v58, v82, v28
	v_fmac_f32_e32 v59, v82, v29
	v_fmac_f32_e32 v60, v82, v32
	v_fmac_f32_e32 v61, v82, v33
	v_fmac_f32_e32 v62, v82, v36
	v_fmac_f32_e32 v63, v82, v37
	v_fmac_f32_e32 v64, v82, v38
	v_fmac_f32_e32 v65, v82, v39
	v_fmac_f32_e32 v66, v82, v34
	v_fmac_f32_e32 v67, v82, v35
	v_fmac_f32_e32 v68, v82, v30
	v_fmac_f32_e32 v70, v82, v26
	v_fmac_f32_e32 v71, v82, v27
	s_waitcnt lgkmcnt(2)
	v_fmac_f32_e32 v75, v82, v22
	v_fmac_f32_e32 v46, v81, v13
	v_fmac_f32_e32 v69, v81, v26
	v_fmac_f32_e32 v44, v80, v12
	v_fmac_f32_e32 v45, v80, v13
	v_fmac_f32_e32 v43, v79, v12
	v_fmac_f32_e32 v42, v78, v12
	v_fmac_f32_e32 v41, v77, v12
	v_fmac_f32_e32 v47, v81, v8
	v_fmac_f32_e32 v48, v81, v9
	v_fmac_f32_e32 v49, v81, v10
	v_fmac_f32_e32 v50, v81, v11
	v_fmac_f32_e32 v51, v81, v14
	v_fmac_f32_e32 v52, v81, v15
	v_fmac_f32_e32 v53, v81, v20
	v_fmac_f32_e32 v54, v81, v21
	v_fmac_f32_e32 v55, v81, v24
	v_fmac_f32_e32 v56, v81, v25
	v_fmac_f32_e32 v57, v81, v28
	v_fmac_f32_e32 v58, v81, v29
	v_fmac_f32_e32 v59, v81, v32
	v_fmac_f32_e32 v60, v81, v33
	v_fmac_f32_e32 v61, v81, v36
	v_fmac_f32_e32 v62, v81, v37
	v_fmac_f32_e32 v63, v81, v38
	v_fmac_f32_e32 v64, v81, v39
	v_fmac_f32_e32 v65, v81, v34
	v_fmac_f32_e32 v66, v81, v35
	v_fmac_f32_e32 v67, v81, v30
	v_fmac_f32_e32 v68, v81, v31
	v_fmac_f32_e32 v70, v81, v27
	v_fmac_f32_e32 v71, v81, v22
	v_fmac_f32_e32 v75, v81, v23
	v_fmac_f32_e32 v46, v80, v8
	v_fmac_f32_e32 v69, v80, v27
	v_fmac_f32_e32 v44, v79, v13
	v_fmac_f32_e32 v45, v79, v8
	v_fmac_f32_e32 v43, v78, v13
	v_fmac_f32_e32 v42, v77, v13
	v_fmac_f32_e32 v41, v76, v13
	ds_read2st64_b32 v[12:13], v40 offset0:240 offset1:244
	v_fmac_f32_e32 v47, v80, v9
	v_fmac_f32_e32 v48, v80, v10
	v_fmac_f32_e32 v49, v80, v11
	v_fmac_f32_e32 v50, v80, v14
	v_fmac_f32_e32 v51, v80, v15
	v_fmac_f32_e32 v52, v80, v20
	v_fmac_f32_e32 v53, v80, v21
	v_fmac_f32_e32 v54, v80, v24
	v_fmac_f32_e32 v55, v80, v25
	v_fmac_f32_e32 v56, v80, v28
	v_fmac_f32_e32 v57, v80, v29
	v_fmac_f32_e32 v58, v80, v32
	v_fmac_f32_e32 v59, v80, v33
	v_fmac_f32_e32 v60, v80, v36
	v_fmac_f32_e32 v61, v80, v37
	v_fmac_f32_e32 v62, v80, v38
	v_fmac_f32_e32 v63, v80, v39
	v_fmac_f32_e32 v64, v80, v34
	v_fmac_f32_e32 v65, v80, v35
	v_fmac_f32_e32 v66, v80, v30
	v_fmac_f32_e32 v67, v80, v31
	v_fmac_f32_e32 v68, v80, v26
	v_fmac_f32_e32 v70, v80, v22
	v_fmac_f32_e32 v71, v80, v23
	s_waitcnt lgkmcnt(2)
	v_fmac_f32_e32 v75, v80, v18
	v_fmac_f32_e32 v46, v79, v9
	v_fmac_f32_e32 v69, v79, v22
	v_fmac_f32_e32 v45, v78, v9
	v_fmac_f32_e32 v47, v79, v10
	v_fmac_f32_e32 v48, v79, v11
	v_fmac_f32_e32 v49, v79, v14
	v_fmac_f32_e32 v50, v79, v15
	v_fmac_f32_e32 v51, v79, v20
	v_fmac_f32_e32 v52, v79, v21
	v_fmac_f32_e32 v53, v79, v24
	v_fmac_f32_e32 v54, v79, v25
	v_fmac_f32_e32 v55, v79, v28
	v_fmac_f32_e32 v56, v79, v29
	v_fmac_f32_e32 v57, v79, v32
	v_fmac_f32_e32 v58, v79, v33
	v_fmac_f32_e32 v59, v79, v36
	v_fmac_f32_e32 v60, v79, v37
	v_fmac_f32_e32 v61, v79, v38
	v_fmac_f32_e32 v62, v79, v39
	v_fmac_f32_e32 v63, v79, v34
	v_fmac_f32_e32 v64, v79, v35
	v_fmac_f32_e32 v65, v79, v30
	v_fmac_f32_e32 v66, v79, v31
	v_fmac_f32_e32 v67, v79, v26
	v_fmac_f32_e32 v68, v79, v27
	v_fmac_f32_e32 v70, v79, v23
	v_fmac_f32_e32 v71, v79, v18
	v_fmac_f32_e32 v75, v79, v19
	v_fmac_f32_e32 v46, v78, v10
	v_fmac_f32_e32 v69, v78, v23
	v_fmac_f32_e32 v45, v77, v10
	v_fmac_f32_e32 v44, v78, v8
	v_fmac_f32_e32 v47, v78, v11
	v_fmac_f32_e32 v48, v78, v14
	v_fmac_f32_e32 v49, v78, v15
	v_fmac_f32_e32 v50, v78, v20
	v_fmac_f32_e32 v51, v78, v21
	v_fmac_f32_e32 v52, v78, v24
	v_fmac_f32_e32 v53, v78, v25
	v_fmac_f32_e32 v54, v78, v28
	v_fmac_f32_e32 v55, v78, v29
	v_fmac_f32_e32 v56, v78, v32
	v_fmac_f32_e32 v57, v78, v33
	v_fmac_f32_e32 v58, v78, v36
	v_fmac_f32_e32 v59, v78, v37
	v_fmac_f32_e32 v60, v78, v38
	v_fmac_f32_e32 v61, v78, v39
	v_fmac_f32_e32 v62, v78, v34
	v_fmac_f32_e32 v63, v78, v35
	v_fmac_f32_e32 v64, v78, v30
	v_fmac_f32_e32 v65, v78, v31
	v_fmac_f32_e32 v66, v78, v26
	v_fmac_f32_e32 v67, v78, v27
	v_fmac_f32_e32 v68, v78, v22
	v_fmac_f32_e32 v70, v78, v18
	v_fmac_f32_e32 v71, v78, v19
	s_waitcnt lgkmcnt(1)
	v_fmac_f32_e32 v75, v78, v16
	v_fmac_f32_e32 v43, v77, v8
	v_fmac_f32_e32 v46, v77, v11
	v_fmac_f32_e32 v69, v77, v18
	v_fmac_f32_e32 v42, v76, v8
	v_fmac_f32_e32 v45, v76, v11
	v_fmac_f32_e32 v41, v74, v8
	v_and_b32_e32 v8, 0xffffffcf, v122
	v_fmac_f32_e32 v44, v77, v9
	v_fmac_f32_e32 v47, v77, v14
	v_fmac_f32_e32 v48, v77, v15
	v_fmac_f32_e32 v49, v77, v20
	v_fmac_f32_e32 v50, v77, v21
	v_fmac_f32_e32 v51, v77, v24
	v_fmac_f32_e32 v52, v77, v25
	v_fmac_f32_e32 v53, v77, v28
	v_fmac_f32_e32 v54, v77, v29
	v_fmac_f32_e32 v55, v77, v32
	v_fmac_f32_e32 v56, v77, v33
	v_fmac_f32_e32 v57, v77, v36
	v_fmac_f32_e32 v58, v77, v37
	v_fmac_f32_e32 v59, v77, v38
	v_fmac_f32_e32 v60, v77, v39
	v_fmac_f32_e32 v61, v77, v34
	v_fmac_f32_e32 v62, v77, v35
	v_fmac_f32_e32 v63, v77, v30
	v_fmac_f32_e32 v64, v77, v31
	v_fmac_f32_e32 v65, v77, v26
	v_fmac_f32_e32 v66, v77, v27
	v_fmac_f32_e32 v67, v77, v22
	v_fmac_f32_e32 v68, v77, v23
	v_fmac_f32_e32 v70, v77, v19
	v_fmac_f32_e32 v71, v77, v16
	v_fmac_f32_e32 v75, v77, v17
	v_fmac_f32_e32 v43, v76, v9
	v_fmac_f32_e32 v46, v76, v14
	v_fmac_f32_e32 v69, v76, v19
	v_fmac_f32_e32 v42, v74, v9
	v_fmac_f32_e32 v45, v74, v14
	v_ashrrev_i32_e32 v9, 31, v8
	v_or_b32_e32 v14, 16, v8
	v_fmac_f32_e32 v44, v76, v10
	v_fmac_f32_e32 v47, v76, v15
	v_fmac_f32_e32 v48, v76, v20
	v_fmac_f32_e32 v49, v76, v21
	v_fmac_f32_e32 v50, v76, v24
	v_fmac_f32_e32 v51, v76, v25
	v_fmac_f32_e32 v52, v76, v28
	v_fmac_f32_e32 v53, v76, v29
	v_fmac_f32_e32 v54, v76, v32
	v_fmac_f32_e32 v55, v76, v33
	v_fmac_f32_e32 v56, v76, v36
	v_fmac_f32_e32 v57, v76, v37
	v_fmac_f32_e32 v58, v76, v38
	v_fmac_f32_e32 v59, v76, v39
	v_fmac_f32_e32 v60, v76, v34
	v_fmac_f32_e32 v61, v76, v35
	v_fmac_f32_e32 v62, v76, v30
	v_fmac_f32_e32 v63, v76, v31
	v_fmac_f32_e32 v64, v76, v26
	v_fmac_f32_e32 v65, v76, v27
	v_fmac_f32_e32 v66, v76, v22
	v_fmac_f32_e32 v67, v76, v23
	v_fmac_f32_e32 v68, v76, v18
	v_fmac_f32_e32 v70, v76, v16
	v_fmac_f32_e32 v71, v76, v17
	s_waitcnt lgkmcnt(0)
	v_fmac_f32_e32 v75, v76, v12
	v_fmac_f32_e32 v46, v74, v15
	v_fmac_f32_e32 v69, v74, v16
	v_and_b32_e32 v200, 48, v123
	v_lshlrev_b64 v[106:107], 9, v[8:9]
	v_ashrrev_i32_e32 v15, 31, v14
	v_or_b32_e32 v8, 32, v8
	v_or_b32_e32 v16, 48, v122
	v_fmac_f32_e32 v43, v74, v10
	v_fmac_f32_e32 v44, v74, v11
	v_fmac_f32_e32 v47, v74, v20
	v_fmac_f32_e32 v48, v74, v21
	v_fmac_f32_e32 v49, v74, v24
	v_fmac_f32_e32 v50, v74, v25
	v_fmac_f32_e32 v51, v74, v28
	v_fmac_f32_e32 v52, v74, v29
	v_fmac_f32_e32 v53, v74, v32
	v_fmac_f32_e32 v54, v74, v33
	v_fmac_f32_e32 v55, v74, v36
	v_fmac_f32_e32 v56, v74, v37
	v_fmac_f32_e32 v57, v74, v38
	v_fmac_f32_e32 v58, v74, v39
	v_fmac_f32_e32 v59, v74, v34
	v_fmac_f32_e32 v60, v74, v35
	v_fmac_f32_e32 v61, v74, v30
	v_fmac_f32_e32 v62, v74, v31
	v_fmac_f32_e32 v63, v74, v26
	v_fmac_f32_e32 v64, v74, v27
	v_fmac_f32_e32 v65, v74, v22
	v_fmac_f32_e32 v66, v74, v23
	v_fmac_f32_e32 v67, v74, v18
	v_fmac_f32_e32 v68, v74, v19
	v_fmac_f32_e32 v70, v74, v17
	v_fmac_f32_e32 v71, v74, v12
	v_fmac_f32_e32 v75, v74, v13
	s_waitcnt lgkmcnt(0)
	s_barrier
	ds_write2st64_b32 v40, v41, v42 offset1:4
	ds_write2st64_b32 v40, v43, v44 offset0:8 offset1:12
	ds_write2st64_b32 v40, v45, v46 offset0:16 offset1:20
	ds_write2st64_b32 v40, v47, v48 offset0:24 offset1:28
	ds_write2st64_b32 v40, v49, v50 offset0:32 offset1:36
	ds_write2st64_b32 v40, v51, v52 offset0:40 offset1:44
	ds_write2st64_b32 v40, v53, v54 offset0:48 offset1:52
	ds_write2st64_b32 v40, v55, v56 offset0:56 offset1:60
	ds_write2st64_b32 v40, v57, v58 offset0:64 offset1:68
	ds_write2st64_b32 v40, v59, v60 offset0:72 offset1:76
	ds_write2st64_b32 v40, v61, v62 offset0:80 offset1:84
	ds_write2st64_b32 v40, v63, v64 offset0:88 offset1:92
	ds_write2st64_b32 v40, v65, v66 offset0:96 offset1:100
	ds_write2st64_b32 v40, v67, v68 offset0:104 offset1:108
	ds_write2st64_b32 v40, v69, v70 offset0:112 offset1:116
	ds_write2st64_b32 v40, v71, v75 offset0:120 offset1:124
	v_lshl_add_u64 v[10:11], s[86:87], 0, v[200:201]
	v_lshlrev_b64 v[110:111], 9, v[14:15]
	v_ashrrev_i32_e32 v9, 31, v8
	v_ashrrev_i32_e32 v17, 31, v16
	s_waitcnt lgkmcnt(0)
	s_barrier
	v_lshl_add_u64 v[12:13], v[10:11], 0, v[106:107]
	v_lshl_add_u64 v[14:15], v[10:11], 0, v[110:111]
	v_lshlrev_b64 v[112:113], 9, v[8:9]
	v_lshlrev_b64 v[108:109], 9, v[16:17]
	v_lshl_add_u32 v114, v124, 13, v102
	v_lshl_add_u64 v[8:9], v[10:11], 0, v[112:113]
	v_lshl_add_u64 v[10:11], v[10:11], 0, v[108:109]
	global_load_dwordx4 v[56:59], v[12:13], off
	global_load_dwordx4 v[40:43], v[12:13], off offset:64
	global_load_dwordx4 v[60:63], v[14:15], off
	global_load_dwordx4 v[44:47], v[14:15], off offset:64
	global_load_dwordx4 v[64:67], v[8:9], off
	global_load_dwordx4 v[48:51], v[8:9], off offset:64
	global_load_dwordx4 v[68:71], v[10:11], off
	global_load_dwordx4 v[52:55], v[10:11], off offset:64
	global_load_dwordx4 v[24:27], v[12:13], off offset:128
	global_load_dwordx4 v[20:23], v[12:13], off offset:192
	global_load_dwordx4 v[28:31], v[14:15], off offset:128
	s_nop 0
	global_load_dwordx4 v[12:15], v[14:15], off offset:192
	ds_read_b128 v[100:103], v114
	global_load_dwordx4 v[32:35], v[8:9], off offset:128
	global_load_dwordx4 v[16:19], v[8:9], off offset:192
	global_load_dwordx4 v[36:39], v[10:11], off offset:128
	s_nop 0
	global_load_dwordx4 v[8:11], v[10:11], off offset:192
	ds_read_b128 v[96:99], v114 offset:1024
	ds_read_b128 v[92:95], v114 offset:2048
	ds_read_b128 v[88:91], v114 offset:3072
	ds_read_b128 v[84:87], v114 offset:4096
	s_waitcnt lgkmcnt(4)
	v_mov_b32_e32 v72, v101
	v_mov_b32_e32 v73, v102
	v_mov_b32_e32 v74, v100
	v_mov_b32_e32 v75, v103
	v_pk_add_f32 v[72:73], v[72:73], v[74:75]
	s_waitcnt lgkmcnt(3)
	v_mov_b32_e32 v74, v96
	v_add_f32_e32 v118, v72, v73
	v_mov_b32_e32 v72, v97
	v_mov_b32_e32 v73, v98
	v_mov_b32_e32 v75, v99
	v_pk_add_f32 v[72:73], v[72:73], v[74:75]
	s_waitcnt lgkmcnt(2)
	v_mov_b32_e32 v74, v92
	v_add_f32_e32 v119, v72, v73
	v_mov_b32_e32 v72, v93
	v_mov_b32_e32 v73, v94
	v_mov_b32_e32 v75, v95
	v_pk_add_f32 v[72:73], v[72:73], v[74:75]
	ds_read_b128 v[80:83], v114 offset:5120
	ds_read_b128 v[76:79], v114 offset:6144
	v_add_f32_e32 v120, v72, v73
	s_waitcnt lgkmcnt(3)
	v_mov_b32_e32 v72, v89
	v_mov_b32_e32 v73, v90
	v_mov_b32_e32 v74, v88
	v_mov_b32_e32 v75, v91
	v_pk_add_f32 v[72:73], v[72:73], v[74:75]
	s_waitcnt lgkmcnt(2)
	v_mov_b32_e32 v74, v84
	v_add_f32_e32 v121, v72, v73
	v_mov_b32_e32 v72, v85
	v_mov_b32_e32 v73, v86
	v_mov_b32_e32 v75, v87
	v_pk_add_f32 v[72:73], v[72:73], v[74:75]
	s_waitcnt lgkmcnt(1)
	v_mov_b32_e32 v74, v80
	v_add_f32_e32 v126, v72, v73
	v_mov_b32_e32 v72, v81
	v_mov_b32_e32 v73, v82
	v_mov_b32_e32 v75, v83
	v_pk_add_f32 v[72:73], v[72:73], v[74:75]
	s_waitcnt lgkmcnt(0)
	v_mov_b32_e32 v115, v78
	v_add_f32_e32 v127, v72, v73
	ds_read_b128 v[72:75], v114 offset:7168
	v_mov_b32_e32 v114, v77
	v_mov_b32_e32 v116, v76
	v_mov_b32_e32 v117, v79
	v_pk_add_f32 v[114:115], v[114:115], v[116:117]
	s_waitcnt lgkmcnt(0)
	v_mov_b32_e32 v116, v72
	v_add_f32_e32 v128, v114, v115
	v_mov_b32_e32 v114, v73
	v_mov_b32_e32 v115, v74
	v_mov_b32_e32 v117, v75
	v_pk_add_f32 v[114:115], v[114:115], v[116:117]
	v_cmp_lt_i32_e32 vcc, v239, v238
	v_add_f32_e32 v114, v114, v115
	s_mov_b32 s0, 0x358637bd
	v_cndmask_b32_e32 v115, v237, v239, vcc
	v_lshlrev_b32_e32 v125, 2, v115
	ds_bpermute_b32 v116, v125, v119
	ds_bpermute_b32 v130, v125, v126
	ds_bpermute_b32 v115, v125, v118
	ds_bpermute_b32 v117, v125, v120
	ds_bpermute_b32 v131, v125, v127
	ds_bpermute_b32 v129, v125, v121
	ds_bpermute_b32 v132, v125, v128
	v_cmp_lt_i32_e32 vcc, v240, v238
	s_waitcnt lgkmcnt(6)
	v_add_f32_e32 v116, v119, v116
	s_waitcnt lgkmcnt(5)
	v_add_f32_e32 v119, v126, v130
	v_cndmask_b32_e32 v126, v237, v240, vcc
	s_waitcnt lgkmcnt(4)
	v_add_f32_e32 v115, v118, v115
	v_lshlrev_b32_e32 v126, 2, v126
	ds_bpermute_b32 v133, v125, v114
	s_waitcnt lgkmcnt(4)
	v_add_f32_e32 v117, v120, v117
	s_waitcnt lgkmcnt(3)
	v_add_f32_e32 v120, v127, v131
	ds_bpermute_b32 v127, v126, v115
	s_waitcnt lgkmcnt(3)
	v_add_f32_e32 v118, v121, v129
	s_waitcnt lgkmcnt(2)
	v_add_f32_e32 v121, v128, v132
	ds_bpermute_b32 v128, v126, v116
	ds_bpermute_b32 v129, v126, v117
	v_cmp_lt_i32_e32 vcc, v241, v238
	s_waitcnt lgkmcnt(3)
	v_add_f32_e32 v114, v114, v133
	s_waitcnt lgkmcnt(2)
	v_add_f32_e32 v115, v115, v127
	v_cndmask_b32_e32 v127, v237, v241, vcc
	ds_bpermute_b32 v130, v126, v118
	ds_bpermute_b32 v134, v126, v114
	v_lshlrev_b32_e32 v127, 2, v127
	ds_bpermute_b32 v131, v126, v119
	ds_bpermute_b32 v132, v126, v120
	ds_bpermute_b32 v133, v126, v121
	s_waitcnt lgkmcnt(6)
	v_add_f32_e32 v116, v116, v128
	ds_bpermute_b32 v128, v127, v115
	s_waitcnt lgkmcnt(6)
	v_add_f32_e32 v117, v117, v129
	ds_bpermute_b32 v129, v127, v116
	s_waitcnt lgkmcnt(6)
	v_add_f32_e32 v118, v118, v130
	s_waitcnt lgkmcnt(5)
	v_add_f32_e32 v114, v114, v134
	ds_bpermute_b32 v130, v127, v117
	v_cmp_lt_i32_e32 vcc, v242, v238
	s_waitcnt lgkmcnt(5)
	v_add_f32_e32 v119, v119, v131
	s_waitcnt lgkmcnt(4)
	v_add_f32_e32 v120, v120, v132
	s_waitcnt lgkmcnt(3)
	v_add_f32_e32 v121, v121, v133
	ds_bpermute_b32 v131, v127, v118
	ds_bpermute_b32 v135, v127, v114
	s_waitcnt lgkmcnt(4)
	v_add_f32_e32 v115, v115, v128
	v_cndmask_b32_e32 v128, v237, v242, vcc
	ds_bpermute_b32 v132, v127, v119
	ds_bpermute_b32 v133, v127, v120
	ds_bpermute_b32 v134, v127, v121
	v_lshlrev_b32_e32 v128, 2, v128
	s_waitcnt lgkmcnt(6)
	v_add_f32_e32 v116, v116, v129
	ds_bpermute_b32 v129, v128, v115
	s_waitcnt lgkmcnt(6)
	v_add_f32_e32 v117, v117, v130
	ds_bpermute_b32 v130, v128, v116
	s_waitcnt lgkmcnt(6)
	v_add_f32_e32 v118, v118, v131
	s_waitcnt lgkmcnt(5)
	v_add_f32_e32 v114, v114, v135
	ds_bpermute_b32 v131, v128, v117
	s_waitcnt lgkmcnt(5)
	v_add_f32_e32 v119, v119, v132
	s_waitcnt lgkmcnt(4)
	v_add_f32_e32 v120, v120, v133
	s_waitcnt lgkmcnt(3)
	v_add_f32_e32 v121, v121, v134
	ds_bpermute_b32 v132, v128, v118
	ds_bpermute_b32 v136, v128, v114
	v_cmp_lt_i32_e32 vcc, v243, v238
	ds_bpermute_b32 v133, v128, v119
	ds_bpermute_b32 v134, v128, v120
	ds_bpermute_b32 v135, v128, v121
	s_waitcnt lgkmcnt(7)
	v_add_f32_e32 v115, v115, v129
	v_cndmask_b32_e32 v129, v237, v243, vcc
	v_lshlrev_b32_e32 v129, 2, v129
	s_waitcnt lgkmcnt(6)
	v_add_f32_e32 v116, v116, v130
	ds_bpermute_b32 v130, v129, v115
	s_waitcnt lgkmcnt(6)
	v_add_f32_e32 v117, v117, v131
	s_waitcnt lgkmcnt(5)
	v_add_f32_e32 v118, v118, v132
	s_waitcnt lgkmcnt(4)
	v_add_f32_e32 v114, v114, v136
	ds_bpermute_b32 v131, v129, v116
	ds_bpermute_b32 v132, v129, v117
	s_waitcnt lgkmcnt(5)
	v_add_f32_e32 v119, v119, v133
	s_waitcnt lgkmcnt(4)
	v_add_f32_e32 v120, v120, v134
	s_waitcnt lgkmcnt(3)
	v_add_f32_e32 v121, v121, v135
	ds_bpermute_b32 v133, v129, v118
	ds_bpermute_b32 v137, v129, v114
	ds_bpermute_b32 v135, v129, v120
	ds_bpermute_b32 v136, v129, v121
	v_cmp_lt_i32_e32 vcc, v244, v238
	s_waitcnt lgkmcnt(6)
	v_add_f32_e32 v115, v115, v130
	ds_bpermute_b32 v134, v129, v119
	v_cndmask_b32_e32 v130, v237, v244, vcc
	v_lshlrev_b32_e32 v130, 2, v130
	s_waitcnt lgkmcnt(6)
	v_add_f32_e32 v116, v116, v131
	s_waitcnt lgkmcnt(5)
	v_add_f32_e32 v117, v117, v132
	ds_bpermute_b32 v131, v130, v115
	s_waitcnt lgkmcnt(5)
	v_add_f32_e32 v118, v118, v133
	s_waitcnt lgkmcnt(4)
	v_add_f32_e32 v114, v114, v137
	ds_bpermute_b32 v132, v130, v116
	ds_bpermute_b32 v133, v130, v117
	s_waitcnt lgkmcnt(5)
	v_add_f32_e32 v120, v120, v135
	s_waitcnt lgkmcnt(4)
	v_add_f32_e32 v121, v121, v136
	ds_bpermute_b32 v138, v130, v114
	ds_bpermute_b32 v136, v130, v120
	ds_bpermute_b32 v137, v130, v121
	s_waitcnt lgkmcnt(6)
	v_add_f32_e32 v119, v119, v134
	s_waitcnt lgkmcnt(5)
	v_add_f32_e32 v115, v115, v131
	ds_bpermute_b32 v134, v130, v118
	ds_bpermute_b32 v135, v130, v119
	s_waitcnt lgkmcnt(6)
	v_add_f32_e32 v131, v116, v132
	s_waitcnt lgkmcnt(5)
	v_add_f32_e32 v139, v117, v133
	v_fmamk_f32 v133, v115, 0xbb800000, v101
	v_fmamk_f32 v132, v115, 0xbb800000, v100
	v_fmamk_f32 v103, v115, 0xbb800000, v103
	v_fmac_f32_e32 v102, 0xbb800000, v115
	s_waitcnt lgkmcnt(4)
	v_add_f32_e32 v144, v114, v138
	v_pk_mul_f32 v[100:101], v[102:103], v[102:103]
	v_pk_mul_f32 v[114:115], v[132:133], v[132:133]
	s_waitcnt lgkmcnt(3)
	v_add_f32_e32 v142, v120, v136
	s_waitcnt lgkmcnt(2)
	v_add_f32_e32 v143, v121, v137
	v_pk_mov_b32 v[116:117], v[114:115], v[100:101] op_sel:[1,0]
	v_mov_b32_e32 v115, v101
	v_fmamk_f32 v121, v131, 0xbb800000, v97
	v_fmamk_f32 v120, v131, 0xbb800000, v96
	v_fmamk_f32 v99, v131, 0xbb800000, v99
	v_fmac_f32_e32 v98, 0xbb800000, v131
	v_pk_add_f32 v[100:101], v[116:117], v[114:115]
	v_pk_mul_f32 v[96:97], v[98:99], v[98:99]
	v_pk_mul_f32 v[114:115], v[120:121], v[120:121]
	s_waitcnt lgkmcnt(1)
	v_add_f32_e32 v140, v118, v134
	v_pk_mov_b32 v[116:117], v[114:115], v[96:97] op_sel:[1,0]
	v_mov_b32_e32 v115, v97
	s_waitcnt lgkmcnt(0)
	v_add_f32_e32 v141, v119, v135
	v_pk_add_f32 v[118:119], v[116:117], v[114:115]
	v_fmamk_f32 v117, v139, 0xbb800000, v93
	v_fmamk_f32 v116, v139, 0xbb800000, v92
	v_fmamk_f32 v95, v139, 0xbb800000, v95
	v_fmac_f32_e32 v94, 0xbb800000, v139
	v_pk_mul_f32 v[92:93], v[94:95], v[94:95]
	v_pk_mul_f32 v[96:97], v[116:117], v[116:117]
	v_fmamk_f32 v91, v140, 0xbb800000, v91
	v_pk_mov_b32 v[114:115], v[96:97], v[92:93] op_sel:[1,0]
	v_mov_b32_e32 v97, v93
	v_pk_add_f32 v[134:135], v[114:115], v[96:97]
	v_fmamk_f32 v97, v140, 0xbb800000, v89
	v_fmamk_f32 v96, v140, 0xbb800000, v88
	v_fmac_f32_e32 v90, 0xbb800000, v140
	v_pk_mul_f32 v[88:89], v[90:91], v[90:91]
	v_pk_mul_f32 v[92:93], v[96:97], v[96:97]
	v_fmamk_f32 v87, v141, 0xbb800000, v87
	v_pk_mov_b32 v[114:115], v[92:93], v[88:89] op_sel:[1,0]
	v_mov_b32_e32 v93, v89
	v_fmamk_f32 v89, v141, 0xbb800000, v85
	v_fmamk_f32 v88, v141, 0xbb800000, v84
	v_fmac_f32_e32 v86, 0xbb800000, v141
	v_pk_add_f32 v[136:137], v[114:115], v[92:93]
	v_pk_mul_f32 v[84:85], v[86:87], v[86:87]
	v_pk_mul_f32 v[92:93], v[88:89], v[88:89]
	v_fmamk_f32 v81, v142, 0xbb800000, v81
	v_pk_mov_b32 v[114:115], v[92:93], v[84:85] op_sel:[1,0]
	v_mov_b32_e32 v93, v85
	v_mov_b32_e32 v84, v118
	v_mov_b32_e32 v85, v100
	v_mov_b32_e32 v100, v119
	v_pk_add_f32 v[84:85], v[84:85], v[100:101]
	v_pk_add_f32 v[114:115], v[114:115], v[92:93]
	ds_bpermute_b32 v93, v125, v85
	ds_bpermute_b32 v92, v125, v84
	v_fmamk_f32 v80, v142, 0xbb800000, v80
	v_fmamk_f32 v83, v142, 0xbb800000, v83
	v_fmac_f32_e32 v82, 0xbb800000, v142
	v_pk_mul_f32 v[100:101], v[82:83], v[82:83]
	s_waitcnt lgkmcnt(0)
	v_pk_add_f32 v[84:85], v[84:85], v[92:93]
	ds_bpermute_b32 v93, v126, v85
	ds_bpermute_b32 v92, v126, v84
	v_pk_mul_f32 v[118:119], v[80:81], v[80:81]
	v_fmamk_f32 v77, v143, 0xbb800000, v77
	v_pk_mov_b32 v[138:139], v[118:119], v[100:101] op_sel:[1,0]
	v_mov_b32_e32 v119, v101
	s_waitcnt lgkmcnt(0)
	v_pk_add_f32 v[84:85], v[84:85], v[92:93]
	s_nop 1
	v_mov_b32_dpp v93, v85 row_ror:8 row_mask:0xf bank_mask:0xf
	s_nop 1
	v_mov_b32_dpp v92, v84 row_ror:8 row_mask:0xf bank_mask:0xf
	v_fmamk_f32 v76, v143, 0xbb800000, v76
	v_fmamk_f32 v79, v143, 0xbb800000, v79
	v_fmac_f32_e32 v78, 0xbb800000, v143
	v_pk_add_f32 v[118:119], v[138:139], v[118:119]
	s_waitcnt lgkmcnt(0)
	v_pk_add_f32 v[84:85], v[84:85], v[92:93]
	s_nop 1
	v_mov_b32_dpp v93, v85 row_half_mirror row_mask:0xf bank_mask:0xf
	s_nop 1
	v_mov_b32_dpp v93, v93 quad_perm:[3,2,1,0] row_mask:0xf bank_mask:0xf
	s_nop 1
	v_mov_b32_dpp v92, v84 row_half_mirror row_mask:0xf bank_mask:0xf
	s_nop 1
	v_mov_b32_dpp v92, v92 quad_perm:[3,2,1,0] row_mask:0xf bank_mask:0xf
	v_pk_mul_f32 v[100:101], v[78:79], v[78:79]
	v_pk_mul_f32 v[138:139], v[76:77], v[76:77]
	s_mov_b32 s28, 0x3b800000
	v_pk_mov_b32 v[140:141], v[138:139], v[100:101] op_sel:[1,0]
	s_waitcnt lgkmcnt(0)
	v_pk_add_f32 v[84:85], v[84:85], v[92:93]
	v_mov_b32_e32 v139, v101
	s_nop 1
	v_mov_b32_dpp v101, v85 quad_perm:[2,3,0,1] row_mask:0xf bank_mask:0xf
	s_nop 1
	v_mov_b32_dpp v100, v84 quad_perm:[2,3,0,1] row_mask:0xf bank_mask:0xf
	v_fmamk_f32 v73, v144, 0xbb800000, v73
	v_fmamk_f32 v72, v144, 0xbb800000, v72
	v_fmamk_f32 v75, v144, 0xbb800000, v75
	v_fmac_f32_e32 v74, 0xbb800000, v144
	s_waitcnt lgkmcnt(0)
	v_pk_add_f32 v[84:85], v[84:85], v[100:101]
	s_nop 1
	v_mov_b32_dpp v101, v85 quad_perm:[1,0,3,2] row_mask:0xf bank_mask:0xf
	s_nop 1
	v_mov_b32_dpp v100, v84 quad_perm:[1,0,3,2] row_mask:0xf bank_mask:0xf
	v_pk_add_f32 v[92:93], v[140:141], v[138:139]
	v_pk_mul_f32 v[138:139], v[74:75], v[74:75]
	v_pk_mul_f32 v[140:141], v[72:73], v[72:73]
	v_and_b32_e32 v105, 15, v122
	s_waitcnt lgkmcnt(0)
	v_pk_add_f32 v[100:101], v[84:85], v[100:101]
	v_mov_b64_e32 v[84:85], s[0:1]
	v_pk_fma_f32 v[144:145], v[100:101], s[28:29], v[84:85] op_sel_hi:[1,0,0]
	s_mov_b32 s1, 0x800000
	v_mul_f32_e32 v100, 0x4b800000, v145
	v_cmp_gt_f32_e32 vcc, s1, v145
	s_movk_i32 s0, 0x1080
	v_pk_mov_b32 v[142:143], v[140:141], v[138:139] op_sel:[1,0]
	v_cndmask_b32_e32 v100, v145, v100, vcc
	v_rsq_f32_e32 v131, v100
	v_mul_lo_u32 v138, v124, s0
	v_mov_b32_e32 v141, v139
	v_pk_add_f32 v[100:101], v[142:143], v[140:141]
	v_mul_f32_e32 v124, 0x45800000, v131
	v_cndmask_b32_e32 v124, v131, v124, vcc
	v_pk_mul_f32 v[132:133], v[132:133], v[124:125] op_sel_hi:[1,0]
	v_add3_u32 v142, s69, v104, v138
	v_pk_fma_f32 v[132:133], v[0:1], v[132:133], v[4:5]
	v_pk_mul_f32 v[102:103], v[102:103], v[124:125] op_sel_hi:[1,0]
	v_mul_f32_e32 v131, 0xbfb8aa3b, v132
	v_exp_f32_e32 v131, v131
	v_mul_f32_e32 v139, 0xbfb8aa3b, v133
	v_exp_f32_e32 v139, v139
	v_pk_fma_f32 v[102:103], v[2:3], v[102:103], v[6:7]
	v_add_f32_e32 v104, 1.0, v131
	v_rcp_f32_e32 v138, v104
	v_add_f32_e32 v104, 1.0, v139
	v_rcp_f32_e32 v139, v104
	v_mul_f32_e32 v104, 0xbfb8aa3b, v102
	v_exp_f32_e32 v104, v104
	v_mul_f32_e32 v124, 0xbfb8aa3b, v103
	v_exp_f32_e32 v124, v124
	v_mov_b32_e32 v140, v136
	v_mov_b32_e32 v141, v134
	v_mov_b32_e32 v134, v137
	v_pk_add_f32 v[134:135], v[140:141], v[134:135]
	v_add_f32_e32 v104, 1.0, v104
	ds_bpermute_b32 v137, v125, v135
	ds_bpermute_b32 v136, v125, v134
	v_pk_mul_f32 v[132:133], v[132:133], v[138:139]
	v_rcp_f32_e32 v138, v104
	v_add_f32_e32 v104, 1.0, v124
	v_rcp_f32_e32 v139, v104
	v_mul_f32_e32 v104, 0x4b800000, v144
	v_cmp_gt_f32_e32 vcc, s1, v144
	s_waitcnt lgkmcnt(0)
	v_pk_add_f32 v[134:135], v[134:135], v[136:137]
	ds_bpermute_b32 v137, v126, v135
	v_cndmask_b32_e32 v104, v144, v104, vcc
	v_rsq_f32_e32 v104, v104
	ds_bpermute_b32 v136, v126, v134
	v_pk_mul_f32 v[102:103], v[102:103], v[138:139]
	v_cvt_pk_bf16_f32 v132, v132, v133
	v_mul_f32_e32 v124, 0x45800000, v104
	v_cndmask_b32_e32 v104, v104, v124, vcc
	v_pk_mul_f32 v[120:121], v[120:121], v[104:105] op_sel_hi:[1,0]
	s_waitcnt lgkmcnt(0)
	v_pk_add_f32 v[134:135], v[134:135], v[136:137]
	v_pk_fma_f32 v[120:121], v[0:1], v[120:121], v[4:5]
	s_nop 1
	v_mov_b32_dpp v137, v135 row_ror:8 row_mask:0xf bank_mask:0xf
	v_mul_f32_e32 v124, 0xbfb8aa3b, v120
	s_nop 1
	v_mov_b32_dpp v136, v134 row_ror:8 row_mask:0xf bank_mask:0xf
	v_exp_f32_e32 v124, v124
	v_mul_f32_e32 v131, 0xbfb8aa3b, v121
	v_exp_f32_e32 v131, v131
	v_cvt_pk_bf16_f32 v133, v102, v103
	v_add_f32_e32 v124, 1.0, v124
	s_waitcnt lgkmcnt(0)
	v_pk_add_f32 v[134:135], v[134:135], v[136:137]
	v_rcp_f32_e32 v140, v124
	v_add_f32_e32 v124, 1.0, v131
	s_nop 1
	v_mov_b32_dpp v137, v135 row_half_mirror row_mask:0xf bank_mask:0xf
	s_nop 1
	v_mov_b32_dpp v137, v137 quad_perm:[3,2,1,0] row_mask:0xf bank_mask:0xf
	s_nop 1
	v_mov_b32_dpp v136, v134 row_half_mirror row_mask:0xf bank_mask:0xf
	s_nop 1
	v_mov_b32_dpp v136, v136 quad_perm:[3,2,1,0] row_mask:0xf bank_mask:0xf
	v_rcp_f32_e32 v141, v124
	v_pk_mul_f32 v[98:99], v[98:99], v[104:105] op_sel_hi:[1,0]
	s_ashr_i32 s40, s94, 3
	v_pk_fma_f32 v[98:99], v[2:3], v[98:99], v[6:7]
	v_pk_mul_f32 v[102:103], v[120:121], v[140:141]
	s_waitcnt lgkmcnt(0)
	v_pk_add_f32 v[120:121], v[134:135], v[136:137]
	s_nop 1
	v_mov_b32_dpp v135, v121 quad_perm:[2,3,0,1] row_mask:0xf bank_mask:0xf
	s_nop 1
	v_mov_b32_dpp v134, v120 quad_perm:[2,3,0,1] row_mask:0xf bank_mask:0xf
	v_mul_f32_e32 v104, 0xbfb8aa3b, v98
	v_exp_f32_e32 v104, v104
	v_cvt_pk_bf16_f32 v102, v102, v103
	s_lshl_b32 s3, s40, 7
	s_waitcnt lgkmcnt(0)
	v_pk_add_f32 v[120:121], v[120:121], v[134:135]
	s_nop 1
	v_mov_b32_dpp v135, v121 quad_perm:[1,0,3,2] row_mask:0xf bank_mask:0xf
	s_nop 1
	v_mov_b32_dpp v134, v120 quad_perm:[1,0,3,2] row_mask:0xf bank_mask:0xf
	v_add_f32_e32 v103, 1.0, v104
	v_mul_f32_e32 v104, 0xbfb8aa3b, v99
	v_exp_f32_e32 v104, v104
	v_readlane_b32 s44, v253, 3
	s_waitcnt lgkmcnt(0)
	v_pk_add_f32 v[120:121], v[120:121], v[134:135]
	v_rcp_f32_e32 v134, v103
	v_pk_fma_f32 v[120:121], v[120:121], s[28:29], v[84:85] op_sel_hi:[1,0,0]
	v_add_f32_e32 v103, 1.0, v104
	v_mul_f32_e32 v124, 0x4b800000, v121
	v_cmp_gt_f32_e32 vcc, s1, v121
	v_rcp_f32_e32 v135, v103
	v_readlane_b32 s52, v253, 11
	v_cndmask_b32_e32 v121, v121, v124, vcc
	v_rsq_f32_e32 v121, v121
	v_pk_mul_f32 v[98:99], v[98:99], v[134:135]
	v_readlane_b32 s53, v253, 12
	s_mul_i32 s38, s40, 0xb0000
	v_mul_f32_e32 v103, 0x45800000, v121
	v_cndmask_b32_e32 v104, v121, v103, vcc
	v_pk_mul_f32 v[116:117], v[116:117], v[104:105] op_sel_hi:[1,0]
	v_pk_mul_f32 v[94:95], v[94:95], v[104:105] op_sel_hi:[1,0]
	v_pk_fma_f32 v[116:117], v[0:1], v[116:117], v[4:5]
	v_pk_fma_f32 v[94:95], v[2:3], v[94:95], v[6:7]
	v_mul_f32_e32 v103, 0xbfb8aa3b, v116
	v_exp_f32_e32 v103, v103
	v_mul_f32_e32 v121, 0xbfb8aa3b, v117
	v_exp_f32_e32 v121, v121
	v_cmp_gt_f32_e32 vcc, s1, v120
	v_add_f32_e32 v103, 1.0, v103
	v_rcp_f32_e32 v134, v103
	v_add_f32_e32 v103, 1.0, v121
	v_rcp_f32_e32 v135, v103
	v_cvt_pk_bf16_f32 v103, v98, v99
	v_add_u32_e32 v121, 0x8000, v142
	ds_write2_b64 v121, v[132:133], v[102:103] offset1:66
	v_mul_f32_e32 v102, 0xbfb8aa3b, v94
	v_exp_f32_e32 v102, v102
	v_mul_f32_e32 v103, 0xbfb8aa3b, v95
	v_exp_f32_e32 v103, v103
	v_pk_mul_f32 v[98:99], v[116:117], v[134:135]
	v_mov_b32_e32 v116, v118
	v_mov_b32_e32 v117, v114
	v_mov_b32_e32 v114, v119
	v_cvt_pk_bf16_f32 v98, v98, v99
	v_add_f32_e32 v99, 1.0, v102
	v_pk_add_f32 v[114:115], v[116:117], v[114:115]
	v_rcp_f32_e32 v102, v99
	v_add_f32_e32 v99, 1.0, v103
	ds_bpermute_b32 v117, v125, v115
	ds_bpermute_b32 v116, v125, v114
	v_rcp_f32_e32 v103, v99
	v_mul_f32_e32 v99, 0x4b800000, v120
	v_cndmask_b32_e32 v99, v120, v99, vcc
	v_rsq_f32_e32 v104, v99
	v_pk_mul_f32 v[94:95], v[94:95], v[102:103]
	s_waitcnt lgkmcnt(0)
	v_pk_add_f32 v[102:103], v[114:115], v[116:117]
	ds_bpermute_b32 v115, v126, v103
	ds_bpermute_b32 v114, v126, v102
	v_cvt_pk_bf16_f32 v99, v94, v95
	v_mul_f32_e32 v94, 0x45800000, v104
	v_cndmask_b32_e32 v94, v104, v94, vcc
	v_pk_mul_f32 v[96:97], v[96:97], v[94:95] op_sel_hi:[1,0]
	s_waitcnt lgkmcnt(0)
	v_pk_add_f32 v[102:103], v[102:103], v[114:115]
	v_pk_fma_f32 v[96:97], v[0:1], v[96:97], v[4:5]
	s_nop 1
	v_mov_b32_dpp v115, v103 row_ror:8 row_mask:0xf bank_mask:0xf
	v_mul_f32_e32 v95, 0xbfb8aa3b, v96
	v_exp_f32_e32 v95, v95
	s_nop 1
	v_mov_b32_dpp v114, v102 row_ror:8 row_mask:0xf bank_mask:0xf
	s_mul_hi_i32 s39, s3, 0x1600
	v_readlane_b32 s45, v253, 4
	v_add_f32_e32 v95, 1.0, v95
	v_rcp_f32_e32 v116, v95
	v_mul_f32_e32 v95, 0xbfb8aa3b, v97
	s_waitcnt lgkmcnt(0)
	v_pk_add_f32 v[102:103], v[102:103], v[114:115]
	v_exp_f32_e32 v95, v95
	s_nop 1
	v_mov_b32_dpp v115, v103 row_half_mirror row_mask:0xf bank_mask:0xf
	s_nop 1
	v_mov_b32_dpp v115, v115 quad_perm:[3,2,1,0] row_mask:0xf bank_mask:0xf
	s_nop 1
	v_mov_b32_dpp v114, v102 row_half_mirror row_mask:0xf bank_mask:0xf
	s_nop 1
	v_mov_b32_dpp v114, v114 quad_perm:[3,2,1,0] row_mask:0xf bank_mask:0xf
	v_readlane_b32 s46, v253, 5
	v_add_f32_e32 v95, 1.0, v95
	v_rcp_f32_e32 v117, v95
	v_pk_mul_f32 v[90:91], v[90:91], v[94:95] op_sel_hi:[1,0]
	s_waitcnt lgkmcnt(0)
	v_pk_add_f32 v[94:95], v[102:103], v[114:115]
	s_nop 1
	v_mov_b32_dpp v103, v95 quad_perm:[2,3,0,1] row_mask:0xf bank_mask:0xf
	s_nop 1
	v_mov_b32_dpp v102, v94 quad_perm:[2,3,0,1] row_mask:0xf bank_mask:0xf
	v_pk_fma_f32 v[90:91], v[2:3], v[90:91], v[6:7]
	v_pk_mul_f32 v[96:97], v[96:97], v[116:117]
	v_mul_f32_e32 v104, 0xbfb8aa3b, v90
	v_exp_f32_e32 v104, v104
	s_waitcnt lgkmcnt(0)
	v_pk_add_f32 v[94:95], v[94:95], v[102:103]
	s_nop 1
	v_mov_b32_dpp v103, v95 quad_perm:[1,0,3,2] row_mask:0xf bank_mask:0xf
	s_nop 1
	v_mov_b32_dpp v102, v94 quad_perm:[1,0,3,2] row_mask:0xf bank_mask:0xf
	v_mul_f32_e32 v114, 0xbfb8aa3b, v91
	v_exp_f32_e32 v115, v114
	v_cvt_pk_bf16_f32 v96, v96, v97
	v_add_f32_e32 v104, 1.0, v104
	s_waitcnt lgkmcnt(0)
	v_pk_add_f32 v[94:95], v[94:95], v[102:103]
	v_rcp_f32_e32 v114, v104
	v_pk_fma_f32 v[94:95], v[94:95], s[28:29], v[84:85] op_sel_hi:[1,0,0]
	v_add_f32_e32 v104, 1.0, v115
	v_mul_f32_e32 v102, 0x4b800000, v95
	v_cmp_gt_f32_e32 vcc, s1, v95
	v_rcp_f32_e32 v115, v104
	v_readlane_b32 s47, v253, 6
	v_cndmask_b32_e32 v95, v95, v102, vcc
	v_rsq_f32_e32 v95, v95
	v_pk_mul_f32 v[90:91], v[90:91], v[114:115]
	v_readlane_b32 s48, v253, 7
	v_readlane_b32 s49, v253, 8
	v_mul_f32_e32 v97, 0x45800000, v95
	v_cndmask_b32_e32 v102, v95, v97, vcc
	v_pk_mul_f32 v[88:89], v[88:89], v[102:103] op_sel_hi:[1,0]
	v_cmp_gt_f32_e32 vcc, s1, v94
	v_pk_fma_f32 v[88:89], v[0:1], v[88:89], v[4:5]
	v_readlane_b32 s50, v253, 9
	v_mul_f32_e32 v95, 0xbfb8aa3b, v88
	v_mul_f32_e32 v97, 0xbfb8aa3b, v89
	v_exp_f32_e32 v95, v95
	v_exp_f32_e32 v103, v97
	v_cvt_pk_bf16_f32 v97, v90, v91
	ds_write2_b64 v121, v[98:99], v[96:97] offset0:132 offset1:198
	v_add_f32_e32 v90, 1.0, v95
	v_add_f32_e32 v91, 1.0, v103
	v_rcp_f32_e32 v90, v90
	v_rcp_f32_e32 v91, v91
	v_pk_mul_f32 v[86:87], v[86:87], v[102:103] op_sel_hi:[1,0]
	v_readlane_b32 s51, v253, 10
	v_pk_fma_f32 v[86:87], v[2:3], v[86:87], v[6:7]
	v_pk_mul_f32 v[88:89], v[88:89], v[90:91]
	v_mov_b32_e32 v90, v100
	v_mov_b32_e32 v91, v92
	v_mov_b32_e32 v92, v101
	v_pk_add_f32 v[90:91], v[90:91], v[92:93]
	ds_bpermute_b32 v93, v125, v91
	ds_bpermute_b32 v92, v125, v90
	v_cvt_pk_bf16_f32 v88, v88, v89
	v_mul_f32_e32 v89, 0x4b800000, v94
	v_mul_f32_e32 v95, 0xbfb8aa3b, v86
	v_cndmask_b32_e32 v89, v94, v89, vcc
	s_waitcnt lgkmcnt(0)
	v_pk_add_f32 v[90:91], v[90:91], v[92:93]
	ds_bpermute_b32 v93, v126, v91
	ds_bpermute_b32 v92, v126, v90
	v_exp_f32_e32 v95, v95
	v_mul_f32_e32 v102, 0xbfb8aa3b, v87
	v_rsq_f32_e32 v89, v89
	v_exp_f32_e32 v103, v102
	s_waitcnt lgkmcnt(0)
	v_pk_add_f32 v[90:91], v[90:91], v[92:93]
	v_add_f32_e32 v95, 1.0, v95
	v_mul_f32_e32 v94, 0x45800000, v89
	s_nop 1
	v_mov_b32_dpp v93, v91 row_ror:8 row_mask:0xf bank_mask:0xf
	s_nop 1
	v_mov_b32_dpp v92, v90 row_ror:8 row_mask:0xf bank_mask:0xf
	v_rcp_f32_e32 v102, v95
	v_add_f32_e32 v95, 1.0, v103
	v_cndmask_b32_e32 v94, v89, v94, vcc
	v_pk_mul_f32 v[80:81], v[80:81], v[94:95] op_sel_hi:[1,0]
	v_rcp_f32_e32 v103, v95
	v_pk_fma_f32 v[80:81], v[0:1], v[80:81], v[4:5]
	s_waitcnt lgkmcnt(0)
	v_pk_add_f32 v[90:91], v[90:91], v[92:93]
	v_mul_f32_e32 v89, 0xbfb8aa3b, v80
	v_exp_f32_e32 v89, v89
	v_mul_f32_e32 v95, 0xbfb8aa3b, v81
	v_exp_f32_e32 v95, v95
	s_nop 1
	v_mov_b32_dpp v93, v91 row_half_mirror row_mask:0xf bank_mask:0xf
	s_nop 1
	v_mov_b32_dpp v93, v93 quad_perm:[3,2,1,0] row_mask:0xf bank_mask:0xf
	s_nop 1
	v_mov_b32_dpp v92, v90 row_half_mirror row_mask:0xf bank_mask:0xf
	s_nop 1
	v_mov_b32_dpp v92, v92 quad_perm:[3,2,1,0] row_mask:0xf bank_mask:0xf
	v_add_f32_e32 v89, 1.0, v89
	v_pk_mul_f32 v[86:87], v[86:87], v[102:103]
	v_rcp_f32_e32 v96, v89
	v_add_f32_e32 v89, 1.0, v95
	v_rcp_f32_e32 v97, v89
	v_cvt_pk_bf16_f32 v89, v86, v87
	s_waitcnt lgkmcnt(0)
	v_pk_add_f32 v[86:87], v[90:91], v[92:93]
	s_nop 1
	v_mov_b32_dpp v91, v87 quad_perm:[2,3,0,1] row_mask:0xf bank_mask:0xf
	s_nop 1
	v_mov_b32_dpp v90, v86 quad_perm:[2,3,0,1] row_mask:0xf bank_mask:0xf
	v_pk_mul_f32 v[82:83], v[82:83], v[94:95] op_sel_hi:[1,0]
	v_pk_mul_f32 v[80:81], v[80:81], v[96:97]
	v_pk_fma_f32 v[82:83], v[2:3], v[82:83], v[6:7]
	v_cvt_pk_bf16_f32 v80, v80, v81
	s_waitcnt lgkmcnt(0)
	v_pk_add_f32 v[86:87], v[86:87], v[90:91]
	s_nop 1
	v_mov_b32_dpp v91, v87 quad_perm:[1,0,3,2] row_mask:0xf bank_mask:0xf
	s_nop 1
	v_mov_b32_dpp v90, v86 quad_perm:[1,0,3,2] row_mask:0xf bank_mask:0xf
	v_mul_f32_e32 v92, 0xbfb8aa3b, v82
	v_mul_f32_e32 v93, 0xbfb8aa3b, v83
	v_exp_f32_e32 v92, v92
	v_exp_f32_e32 v93, v93
	s_waitcnt lgkmcnt(0)
	v_pk_add_f32 v[86:87], v[86:87], v[90:91]
	v_add_u32_e32 v90, 0x8800, v142
	v_pk_fma_f32 v[84:85], v[86:87], s[28:29], v[84:85] op_sel_hi:[1,0,0]
	v_add_f32_e32 v92, 1.0, v92
	v_add_f32_e32 v93, 1.0, v93
	v_mul_f32_e32 v86, 0x4b800000, v85
	v_cmp_gt_f32_e32 vcc, s1, v85
	v_rcp_f32_e32 v92, v92
	v_rcp_f32_e32 v93, v93
	v_cndmask_b32_e32 v85, v85, v86, vcc
	v_rsq_f32_e32 v85, v85
	v_readlane_b32 s54, v253, 13
	v_pk_mul_f32 v[82:83], v[82:83], v[92:93]
	v_readlane_b32 s55, v253, 14
	v_cvt_pk_bf16_f32 v81, v82, v83
	v_mul_f32_e32 v82, 0x45800000, v85
	v_cndmask_b32_e32 v82, v85, v82, vcc
	v_pk_mul_f32 v[76:77], v[76:77], v[82:83] op_sel_hi:[1,0]
	ds_write2_b64 v90, v[88:89], v[80:81] offset0:8 offset1:74
	v_pk_fma_f32 v[76:77], v[0:1], v[76:77], v[4:5]
	v_cmp_gt_f32_e32 vcc, s1, v84
	v_mul_f32_e32 v83, 0xbfb8aa3b, v76
	v_exp_f32_e32 v83, v83
	v_mul_f32_e32 v85, 0xbfb8aa3b, v77
	v_exp_f32_e32 v85, v85
	v_readlane_b32 s56, v253, 15
	v_add_f32_e32 v83, 1.0, v83
	v_rcp_f32_e32 v86, v83
	v_add_f32_e32 v83, 1.0, v85
	v_pk_mul_f32 v[78:79], v[78:79], v[82:83] op_sel_hi:[1,0]
	v_rcp_f32_e32 v87, v83
	v_pk_fma_f32 v[78:79], v[2:3], v[78:79], v[6:7]
	v_readlane_b32 s57, v253, 16
	v_mul_f32_e32 v82, 0xbfb8aa3b, v78
	v_exp_f32_e32 v82, v82
	v_mul_f32_e32 v80, 0xbfb8aa3b, v79
	v_exp_f32_e32 v81, v80
	v_mul_f32_e32 v80, 0x4b800000, v84
	v_pk_mul_f32 v[76:77], v[76:77], v[86:87]
	v_cndmask_b32_e32 v80, v84, v80, vcc
	v_cvt_pk_bf16_f32 v76, v76, v77
	v_add_f32_e32 v77, 1.0, v82
	v_rsq_f32_e32 v82, v80
	v_rcp_f32_e32 v80, v77
	v_add_f32_e32 v77, 1.0, v81
	v_rcp_f32_e32 v81, v77
	v_mul_f32_e32 v77, 0x45800000, v82
	v_cndmask_b32_e32 v82, v82, v77, vcc
	v_pk_mul_f32 v[72:73], v[72:73], v[82:83] op_sel_hi:[1,0]
	v_pk_mul_f32 v[74:75], v[74:75], v[82:83] op_sel_hi:[1,0]
	v_pk_fma_f32 v[0:1], v[0:1], v[72:73], v[4:5]
	v_pk_fma_f32 v[2:3], v[2:3], v[74:75], v[6:7]
	v_mul_f32_e32 v4, 0xbfb8aa3b, v0
	v_exp_f32_e32 v72, v4
	v_mul_f32_e32 v4, 0xbfb8aa3b, v1
	v_mul_f32_e32 v6, 0xbfb8aa3b, v2
	v_mul_f32_e32 v7, 0xbfb8aa3b, v3
	v_exp_f32_e32 v73, v4
	v_exp_f32_e32 v6, v6
	v_exp_f32_e32 v7, v7
	v_add_f32_e32 v72, 1.0, v72
	v_add_f32_e32 v73, 1.0, v73
	v_add_f32_e32 v6, 1.0, v6
	v_add_f32_e32 v7, 1.0, v7
	v_rcp_f32_e32 v72, v72
	v_rcp_f32_e32 v73, v73
	v_rcp_f32_e32 v6, v6
	v_rcp_f32_e32 v7, v7
	v_pk_mul_f32 v[4:5], v[78:79], v[80:81]
	v_pk_mul_f32 v[0:1], v[0:1], v[72:73]
	v_cvt_pk_bf16_f32 v77, v4, v5
	v_pk_mul_f32 v[2:3], v[2:3], v[6:7]
	v_cvt_pk_bf16_f32 v0, v0, v1
	v_cvt_pk_bf16_f32 v1, v2, v3
	ds_write2_b64 v90, v[76:77], v[0:1] offset0:140 offset1:206
	v_and_b32_e32 v0, 48, v122
	v_mul_u32_u24_e32 v1, 0x210, v105
	s_waitcnt lgkmcnt(0)
	s_barrier
	v_add3_u32 v92, s69, v0, v1
	ds_read_b128 v[0:3], v92 offset:32768
	ds_read_b128 v[4:7], v92 offset:32832
	ds_read_b128 v[84:87], v92 offset:41216
	ds_read_b128 v[88:91], v92 offset:41280
	s_waitcnt vmcnt(15) lgkmcnt(3)
	v_mfma_f32_16x16x32_bf16 v[72:75], v[0:3], v[56:59], 0
	v_readlane_b32 s58, v253, 17
	v_readlane_b32 s59, v253, 18
	s_waitcnt vmcnt(13)
	v_mfma_f32_16x16x32_bf16 v[76:79], v[0:3], v[60:63], 0
	s_waitcnt vmcnt(11)
	v_mfma_f32_16x16x32_bf16 v[80:83], v[0:3], v[64:67], 0
	s_waitcnt vmcnt(9)
	v_mfma_f32_16x16x32_bf16 v[0:3], v[0:3], v[68:71], 0
	s_waitcnt lgkmcnt(1)
	v_mfma_f32_16x16x32_bf16 v[56:59], v[84:87], v[56:59], 0
	v_mfma_f32_16x16x32_bf16 v[60:63], v[84:87], v[60:63], 0
	v_mfma_f32_16x16x32_bf16 v[64:67], v[84:87], v[64:67], 0
	v_mfma_f32_16x16x32_bf16 v[68:71], v[84:87], v[68:71], 0
	v_mfma_f32_16x16x32_bf16 v[72:75], v[4:7], v[40:43], v[72:75]
	v_mfma_f32_16x16x32_bf16 v[76:79], v[4:7], v[44:47], v[76:79]
	v_mfma_f32_16x16x32_bf16 v[80:83], v[4:7], v[48:51], v[80:83]
	s_waitcnt vmcnt(8)
	v_mfma_f32_16x16x32_bf16 v[0:3], v[4:7], v[52:55], v[0:3]
	s_waitcnt lgkmcnt(0)
	v_mfma_f32_16x16x32_bf16 v[4:7], v[88:91], v[40:43], v[56:59]
	v_mfma_f32_16x16x32_bf16 v[40:43], v[88:91], v[44:47], v[60:63]
	v_mfma_f32_16x16x32_bf16 v[44:47], v[88:91], v[48:51], v[64:67]
	v_mfma_f32_16x16x32_bf16 v[48:51], v[88:91], v[52:55], v[68:71]
	ds_read_b128 v[52:55], v92 offset:32896
	ds_read_b128 v[56:59], v92 offset:32960
	s_waitcnt vmcnt(7) lgkmcnt(1)
	v_mfma_f32_16x16x32_bf16 v[60:63], v[52:55], v[24:27], v[72:75]
	s_waitcnt vmcnt(5)
	v_mfma_f32_16x16x32_bf16 v[64:67], v[52:55], v[28:31], v[76:79]
	s_waitcnt vmcnt(3)
	v_mfma_f32_16x16x32_bf16 v[68:71], v[52:55], v[32:35], v[80:83]
	s_waitcnt vmcnt(1)
	v_mfma_f32_16x16x32_bf16 v[0:3], v[52:55], v[36:39], v[0:3]
	ds_read_b128 v[52:55], v92 offset:41344
	ds_read_b128 v[72:75], v92 offset:41408
	s_waitcnt lgkmcnt(1)
	v_mfma_f32_16x16x32_bf16 v[4:7], v[52:55], v[24:27], v[4:7]
	v_mfma_f32_16x16x32_bf16 v[24:27], v[52:55], v[28:31], v[40:43]
	v_mfma_f32_16x16x32_bf16 v[28:31], v[52:55], v[32:35], v[44:47]
	s_nop 2
	v_lshl_add_u64 v[44:45], s[86:87], 0, v[106:107]
	v_mfma_f32_16x16x32_bf16 v[32:35], v[52:55], v[36:39], v[48:51]
	v_lshl_add_u64 v[76:77], v[44:45], 0, v[200:201]
	v_lshl_add_u64 v[52:53], s[86:87], 0, v[110:111]
	v_lshl_add_u64 v[78:79], v[52:53], 0, v[200:201]
	v_mfma_f32_16x16x32_bf16 v[36:39], v[56:59], v[20:23], v[60:63]
	global_load_dwordx4 v[48:51], v[76:77], off offset:256
	global_load_dwordx4 v[52:55], v[78:79], off offset:256
	s_nop 0
	global_load_dwordx4 v[60:63], v[78:79], off offset:320
	v_mfma_f32_16x16x32_bf16 v[40:43], v[56:59], v[12:15], v[64:67]
	v_mfma_f32_16x16x32_bf16 v[44:47], v[56:59], v[16:19], v[68:71]
	s_waitcnt vmcnt(3)
	v_mfma_f32_16x16x32_bf16 v[0:3], v[56:59], v[8:11], v[0:3]
	v_lshl_add_u64 v[56:57], s[86:87], 0, v[112:113]
	v_lshl_add_u64 v[80:81], v[56:57], 0, v[200:201]
	v_lshl_add_u64 v[56:57], s[86:87], 0, v[108:109]
	v_lshl_add_u64 v[82:83], v[56:57], 0, v[200:201]
	s_waitcnt lgkmcnt(0)
	v_mfma_f32_16x16x32_bf16 v[4:7], v[72:75], v[20:23], v[4:7]
	global_load_dwordx4 v[20:23], v[80:81], off offset:256
	global_load_dwordx4 v[64:67], v[80:81], off offset:320
	global_load_dwordx4 v[68:71], v[82:83], off offset:320
	v_mfma_f32_16x16x32_bf16 v[12:15], v[72:75], v[12:15], v[24:27]
	ds_read_b128 v[56:59], v92 offset:33088
	v_lshlrev_b32_e32 v200, 1, v105
	s_nop 0
	global_load_dwordx4 v[24:27], v[82:83], off offset:256
	v_mfma_f32_16x16x32_bf16 v[8:11], v[72:75], v[8:11], v[32:35]
	s_nop 2
	global_load_dwordx4 v[32:35], v[76:77], off offset:320
	v_mfma_f32_16x16x32_bf16 v[16:19], v[72:75], v[16:19], v[28:31]
	s_nop 2
	ds_read_b128 v[28:31], v92 offset:33024
	s_waitcnt vmcnt(7) lgkmcnt(0)
	v_mfma_f32_16x16x32_bf16 v[36:39], v[28:31], v[48:51], v[36:39]
	s_waitcnt vmcnt(6)
	v_mfma_f32_16x16x32_bf16 v[40:43], v[28:31], v[52:55], v[40:43]
	s_waitcnt vmcnt(4)
	v_mfma_f32_16x16x32_bf16 v[44:47], v[28:31], v[20:23], v[44:47]
	s_waitcnt vmcnt(1)
	v_mfma_f32_16x16x32_bf16 v[0:3], v[28:31], v[24:27], v[0:3]
	ds_read_b128 v[28:31], v92 offset:41472
	ds_read_b128 v[72:75], v92 offset:41536
	s_waitcnt lgkmcnt(1)
	v_mfma_f32_16x16x32_bf16 v[4:7], v[28:31], v[48:51], v[4:7]
	ds_read_b128 v[48:51], v92 offset:33152
	v_mfma_f32_16x16x32_bf16 v[12:15], v[28:31], v[52:55], v[12:15]
	global_load_dwordx4 v[52:55], v[76:77], off offset:448
	v_mfma_f32_16x16x32_bf16 v[16:19], v[28:31], v[20:23], v[16:19]
	v_mfma_f32_16x16x32_bf16 v[8:11], v[28:31], v[24:27], v[8:11]
	s_waitcnt vmcnt(1)
	v_mfma_f32_16x16x32_bf16 v[20:23], v[56:59], v[32:35], v[36:39]
	v_mfma_f32_16x16x32_bf16 v[24:27], v[56:59], v[60:63], v[40:43]
	s_nop 1
	global_load_dwordx4 v[36:39], v[76:77], off offset:384
	v_mfma_f32_16x16x32_bf16 v[28:31], v[56:59], v[64:67], v[44:47]
	global_load_dwordx4 v[40:43], v[78:79], off offset:384
	s_waitcnt lgkmcnt(1)
	v_mfma_f32_16x16x32_bf16 v[4:7], v[72:75], v[32:35], v[4:7]
	global_load_dwordx4 v[32:35], v[80:81], off offset:384
	global_load_dwordx4 v[44:47], v[82:83], off offset:384
	v_mfma_f32_16x16x32_bf16 v[12:15], v[72:75], v[60:63], v[12:15]
	global_load_dwordx4 v[60:63], v[78:79], off offset:448
	v_mfma_f32_16x16x32_bf16 v[0:3], v[56:59], v[68:71], v[0:3]
	ds_read_b128 v[56:59], v92 offset:33216
	v_mfma_f32_16x16x32_bf16 v[16:19], v[72:75], v[64:67], v[16:19]
	global_load_dwordx4 v[64:67], v[80:81], off offset:448
	v_mfma_f32_16x16x32_bf16 v[8:11], v[72:75], v[68:71], v[8:11]
	global_load_dwordx4 v[68:71], v[82:83], off offset:448
	s_waitcnt vmcnt(6) lgkmcnt(1)
	v_mfma_f32_16x16x32_bf16 v[20:23], v[48:51], v[36:39], v[20:23]
	s_waitcnt vmcnt(5)
	v_mfma_f32_16x16x32_bf16 v[24:27], v[48:51], v[40:43], v[24:27]
	s_waitcnt vmcnt(4)
	v_mfma_f32_16x16x32_bf16 v[28:31], v[48:51], v[32:35], v[28:31]
	s_waitcnt vmcnt(3)
	v_mfma_f32_16x16x32_bf16 v[0:3], v[48:51], v[44:47], v[0:3]
	ds_read_b128 v[48:51], v92 offset:41600
	ds_read_b128 v[72:75], v92 offset:41664
	s_waitcnt lgkmcnt(1)
	v_mfma_f32_16x16x32_bf16 v[16:19], v[48:51], v[32:35], v[16:19]
	v_lshrrev_b32_e32 v32, 2, v123
	v_and_b32_e32 v34, 0xffffffc0, v122
	v_and_or_b32 v32, v32, 12, s2
	v_mfma_f32_16x16x32_bf16 v[20:23], v[56:59], v[52:55], v[20:23]
	v_ashrrev_i32_e32 v35, 31, v34
	v_lshl_add_u64 v[34:35], v[34:35], 1, s[22:23]
	v_ashrrev_i32_e32 v33, 31, v32
	s_waitcnt vmcnt(2)
	v_mfma_f32_16x16x32_bf16 v[24:27], v[56:59], v[60:63], v[24:27]
	v_lshl_add_u64 v[34:35], v[34:35], 0, v[200:201]
	s_nop 1
	v_cvt_pk_bf16_f32 v20, v20, s0
	s_bfe_u32 s2, s94, 0x20001
	s_waitcnt vmcnt(1)
	v_mfma_f32_16x16x32_bf16 v[28:31], v[56:59], v[64:67], v[28:31]
	s_cmp_gt_i32 s40, 31
	s_waitcnt vmcnt(0)
	v_mfma_f32_16x16x32_bf16 v[0:3], v[56:59], v[68:71], v[0:3]
	v_mfma_f32_16x16x32_bf16 v[4:7], v[48:51], v[36:39], v[4:7]
	v_lshlrev_b64 v[36:37], 11, v[32:33]
	v_lshl_add_u64 v[36:37], v[34:35], 0, v[36:37]
	global_store_short v[36:37], v20, off
	v_cvt_pk_bf16_f32 v20, v24, s0
	global_store_short v[36:37], v20, off offset:32
	v_cvt_pk_bf16_f32 v20, v28, s0
	s_nop 0
	v_cvt_pk_bf16_f32 v0, v0, s0
	global_store_short v[36:37], v20, off offset:64
	global_store_short v[36:37], v0, off offset:96
	v_or_b32_e32 v36, 1, v32
	v_ashrrev_i32_e32 v37, 31, v36
	v_lshlrev_b64 v[36:37], 11, v[36:37]
	v_lshl_add_u64 v[36:37], v[34:35], 0, v[36:37]
	v_cvt_pk_bf16_f32 v0, v21, s0
	global_store_short v[36:37], v0, off
	v_cvt_pk_bf16_f32 v0, v25, s0
	global_store_short v[36:37], v0, off offset:32
	v_cvt_pk_bf16_f32 v0, v29, s0
	global_store_short v[36:37], v0, off offset:64
	v_cvt_pk_bf16_f32 v0, v1, s0
	global_store_short v[36:37], v0, off offset:96
	v_or_b32_e32 v0, 2, v32
	v_ashrrev_i32_e32 v1, 31, v0
	v_lshlrev_b64 v[0:1], 11, v[0:1]
	v_lshl_add_u64 v[0:1], v[34:35], 0, v[0:1]
	v_cvt_pk_bf16_f32 v20, v22, s0
	global_store_short v[0:1], v20, off
	v_cvt_pk_bf16_f32 v20, v26, s0
	global_store_short v[0:1], v20, off offset:32
	v_cvt_pk_bf16_f32 v20, v30, s0
	v_cvt_pk_bf16_f32 v2, v2, s0
	global_store_short v[0:1], v20, off offset:64
	global_store_short v[0:1], v2, off offset:96
	v_or_b32_e32 v0, 3, v32
	v_ashrrev_i32_e32 v1, 31, v0
	v_lshlrev_b64 v[0:1], 11, v[0:1]
	v_mfma_f32_16x16x32_bf16 v[12:15], v[48:51], v[40:43], v[12:15]
	v_lshl_add_u64 v[0:1], v[34:35], 0, v[0:1]
	v_cvt_pk_bf16_f32 v2, v23, s0
	global_store_short v[0:1], v2, off
	v_cvt_pk_bf16_f32 v2, v27, s0
	v_mfma_f32_16x16x32_bf16 v[8:11], v[48:51], v[44:47], v[8:11]
	global_store_short v[0:1], v2, off offset:32
	v_cvt_pk_bf16_f32 v2, v31, s0
	global_store_short v[0:1], v2, off offset:64
	s_waitcnt lgkmcnt(0)
	v_mfma_f32_16x16x32_bf16 v[4:7], v[72:75], v[52:55], v[4:7]
	v_cvt_pk_bf16_f32 v2, v3, s0
	global_store_short v[0:1], v2, off offset:96
	v_or_b32_e32 v0, 16, v32
	v_mfma_f32_16x16x32_bf16 v[12:15], v[72:75], v[60:63], v[12:15]
	v_ashrrev_i32_e32 v1, 31, v0
	v_lshlrev_b64 v[0:1], 11, v[0:1]
	v_lshl_add_u64 v[0:1], v[34:35], 0, v[0:1]
	v_mfma_f32_16x16x32_bf16 v[16:19], v[72:75], v[64:67], v[16:19]
	v_cvt_pk_bf16_f32 v2, v4, s0
	global_store_short v[0:1], v2, off
	s_nop 1
	v_cvt_pk_bf16_f32 v2, v12, s0
	v_mfma_f32_16x16x32_bf16 v[8:11], v[72:75], v[68:71], v[8:11]
	global_store_short v[0:1], v2, off offset:32
	s_nop 0
	v_cvt_pk_bf16_f32 v2, v16, s0
	global_store_short v[0:1], v2, off offset:64
	v_mov_b32_e32 v38, v229
	v_mov_b32_e32 v22, v229
	s_nop 1
	v_cvt_pk_bf16_f32 v2, v8, s0
	global_store_short v[0:1], v2, off offset:96
	v_or_b32_e32 v0, 17, v32
	v_ashrrev_i32_e32 v1, 31, v0
	v_lshlrev_b64 v[0:1], 11, v[0:1]
	v_lshl_add_u64 v[0:1], v[34:35], 0, v[0:1]
	v_cvt_pk_bf16_f32 v2, v5, s0
	global_store_short v[0:1], v2, off
	v_cvt_pk_bf16_f32 v2, v13, s0
	global_store_short v[0:1], v2, off offset:32
	v_cvt_pk_bf16_f32 v2, v17, s0
	global_store_short v[0:1], v2, off offset:64
	v_cvt_pk_bf16_f32 v2, v9, s0
	global_store_short v[0:1], v2, off offset:96
	v_or_b32_e32 v0, 18, v32
	v_ashrrev_i32_e32 v1, 31, v0
	v_lshlrev_b64 v[0:1], 11, v[0:1]
	v_lshl_add_u64 v[0:1], v[34:35], 0, v[0:1]
	v_cvt_pk_bf16_f32 v2, v6, s0
	global_store_short v[0:1], v2, off
	v_cvt_pk_bf16_f32 v2, v14, s0
	global_store_short v[0:1], v2, off offset:32
	v_cvt_pk_bf16_f32 v2, v18, s0
	global_store_short v[0:1], v2, off offset:64
	v_cvt_pk_bf16_f32 v2, v10, s0
	global_store_short v[0:1], v2, off offset:96
	v_or_b32_e32 v0, 19, v32
	v_ashrrev_i32_e32 v1, 31, v0
	v_lshlrev_b64 v[0:1], 11, v[0:1]
	v_lshl_add_u64 v[0:1], v[34:35], 0, v[0:1]
	v_cvt_pk_bf16_f32 v2, v7, s0
	global_store_short v[0:1], v2, off
	v_cvt_pk_bf16_f32 v2, v15, s0
	global_store_short v[0:1], v2, off offset:32
	v_cvt_pk_bf16_f32 v2, v19, s0
	global_store_short v[0:1], v2, off offset:64
	v_cvt_pk_bf16_f32 v2, v11, s0
	s_cselect_b64 s[0:1], -1, 0
	s_or_b32 s28, s2, s79
	s_ashr_i32 s29, s28, 31
	s_lshl_b64 s[28:29], s[28:29], 2
	s_add_u32 s28, s52, s28
	s_addc_u32 s29, s53, s29
	global_store_short v[0:1], v2, off offset:96
	s_add_u32 s38, s20, s38
	s_waitcnt lgkmcnt(0)
	s_barrier
	s_addc_u32 s39, s21, s39
	s_lshl_b32 s41, s2, 7
	global_load_dword v41, v201, s[28:29]
	s_add_u32 s38, s38, s41
	v_lshlrev_b32_e32 v0, 2, v22
	v_and_b32_e32 v23, 60, v0
	s_addc_u32 s39, s39, 0
	v_lshlrev_b32_e32 v200, 1, v23
	v_lshl_add_u64 v[0:1], s[38:39], 0, v[200:201]
	s_mov_b64 s[28:29], 0x1200
	v_lshl_add_u64 v[0:1], v[0:1], 0, s[28:29]
	v_ashrrev_i32_e32 v2, 4, v22
	v_mad_i64_i32 v[2:3], s[28:29], v2, s92, v[0:1]
	global_load_dwordx2 v[2:3], v[2:3], off
	v_add_u32_e32 v24, 0x100, v22
	v_ashrrev_i32_e32 v4, 4, v24
	v_mad_i64_i32 v[4:5], s[28:29], v4, s92, v[0:1]
	global_load_dwordx2 v[4:5], v[4:5], off
	v_add_u32_e32 v25, 0x200, v22
	v_ashrrev_i32_e32 v6, 4, v25
	v_mad_i64_i32 v[6:7], s[28:29], v6, s92, v[0:1]
	global_load_dwordx2 v[6:7], v[6:7], off
	v_add_u32_e32 v26, 0x300, v22
	v_ashrrev_i32_e32 v8, 4, v26
	v_mad_i64_i32 v[8:9], s[28:29], v8, s92, v[0:1]
	global_load_dwordx2 v[8:9], v[8:9], off
	v_add_u32_e32 v27, 0x400, v22
	v_ashrrev_i32_e32 v10, 4, v27
	v_mad_i64_i32 v[10:11], s[28:29], v10, s92, v[0:1]
	global_load_dwordx2 v[10:11], v[10:11], off
	v_add_u32_e32 v28, 0x500, v22
	s_lshl_b32 s38, s80, 1
	v_ashrrev_i32_e32 v12, 4, v28
	s_or_b32 s28, s41, s38
	v_mad_i64_i32 v[12:13], s[38:39], v12, s92, v[0:1]
	s_add_u32 s28, s20, s28
	global_load_dwordx2 v[12:13], v[12:13], off
	v_add_u32_e32 v29, 0x600, v22
	v_add_u32_e32 v30, 0x700, v22
	v_bfe_u32 v31, v38, 2, 1
	s_addc_u32 s29, s21, 0
	v_ashrrev_i32_e32 v14, 4, v29
	v_ashrrev_i32_e32 v16, 4, v30
	v_lshlrev_b32_e32 v200, 6, v31
	v_lshlrev_b32_e32 v39, 3, v38
	v_mad_i64_i32 v[14:15], s[38:39], v14, s92, v[0:1]
	v_mad_i64_i32 v[0:1], s[38:39], v16, s92, v[0:1]
	v_lshl_add_u64 v[16:17], s[28:29], 0, v[200:201]
	v_and_b32_e32 v200, 24, v39
	v_ashrrev_i32_e32 v40, 3, v38
	global_load_dwordx2 v[14:15], v[14:15], off
	v_lshl_add_u64 v[16:17], v[16:17], 0, v[200:201]
	v_add_u32_e32 v18, s3, v40
	v_mad_i64_i32 v[18:19], s[28:29], v18, s92, v[16:17]
	global_load_dwordx2 v[0:1], v[0:1], off
	s_nop 0
	global_load_dwordx2 v[20:21], v[18:19], off
	s_nop 0
	global_load_dwordx2 v[18:19], v[18:19], off offset:32
	v_mov_b32_e32 v32, s69
	s_movk_i32 s38, 0x110
	v_ashrrev_i32_e32 v22, 3, v22
	v_mad_u32_u24 v23, v23, s38, v32
	v_and_b32_e32 v22, -2, v22
	v_add_u32_e32 v22, v23, v22
	v_add_u32_e32 v54, 0x100, v38
	v_ashrrev_i32_e32 v42, 3, v54
	v_add_u32_e32 v46, s3, v42
	v_mad_i64_i32 v[48:49], vcc, v46, s92, v[16:17]
	global_load_dwordx2 v[60:61], v[48:49], off
	global_load_dwordx2 v[62:63], v[48:49], off offset:32
	v_add_u32_e32 v55, 0x200, v38
	v_ashrrev_i32_e32 v43, 3, v55
	v_add_u32_e32 v46, s3, v43
	v_mad_i64_i32 v[48:49], vcc, v46, s92, v[16:17]
	global_load_dwordx2 v[64:65], v[48:49], off
	global_load_dwordx2 v[66:67], v[48:49], off offset:32
	v_add_u32_e32 v56, 0x300, v38
	v_ashrrev_i32_e32 v44, 3, v56
	v_add_u32_e32 v46, s3, v44
	v_mad_i64_i32 v[48:49], vcc, v46, s92, v[16:17]
	global_load_dwordx2 v[68:69], v[48:49], off
	global_load_dwordx2 v[70:71], v[48:49], off offset:32
	s_waitcnt vmcnt(15)
	ds_write_b16 v22, v2 offset:17408
	ds_write_b16_d16_hi v22, v2 offset:17680
	ds_write_b16 v22, v3 offset:17952
	ds_write_b16_d16_hi v22, v3 offset:18224
	v_ashrrev_i32_e32 v2, 3, v24
	v_and_b32_e32 v2, -2, v2
	v_add_u32_e32 v2, v23, v2
	s_waitcnt vmcnt(14)
	ds_write_b16 v2, v4 offset:17408
	ds_write_b16_d16_hi v2, v4 offset:17680
	ds_write_b16 v2, v5 offset:17952
	ds_write_b16_d16_hi v2, v5 offset:18224
	v_ashrrev_i32_e32 v2, 3, v25
	v_and_b32_e32 v2, -2, v2
	v_add_u32_e32 v2, v23, v2
	s_waitcnt vmcnt(13)
	ds_write_b16 v2, v6 offset:17408
	ds_write_b16_d16_hi v2, v6 offset:17680
	ds_write_b16 v2, v7 offset:17952
	ds_write_b16_d16_hi v2, v7 offset:18224
	v_ashrrev_i32_e32 v2, 3, v26
	v_and_b32_e32 v2, -2, v2
	v_add_u32_e32 v2, v23, v2
	s_waitcnt vmcnt(12)
	ds_write_b16 v2, v8 offset:17408
	ds_write_b16_d16_hi v2, v8 offset:17680
	ds_write_b16 v2, v9 offset:17952
	ds_write_b16_d16_hi v2, v9 offset:18224
	v_ashrrev_i32_e32 v2, 3, v27
	v_and_b32_e32 v2, -2, v2
	v_add_u32_e32 v2, v23, v2
	s_waitcnt vmcnt(11)
	ds_write_b16 v2, v10 offset:17408
	ds_write_b16_d16_hi v2, v10 offset:17680
	ds_write_b16 v2, v11 offset:17952
	ds_write_b16_d16_hi v2, v11 offset:18224
	v_ashrrev_i32_e32 v2, 3, v28
	v_and_b32_e32 v2, -2, v2
	v_add_u32_e32 v2, v23, v2
	s_waitcnt vmcnt(10)
	ds_write_b16 v2, v12 offset:17408
	ds_write_b16_d16_hi v2, v12 offset:17680
	ds_write_b16 v2, v13 offset:17952
	ds_write_b16_d16_hi v2, v13 offset:18224
	v_ashrrev_i32_e32 v2, 3, v29
	s_cmp_lt_i32 s40, 32
	v_and_b32_e32 v2, -2, v2
	s_cselect_b64 s[28:29], -1, 0
	v_add_u32_e32 v2, v23, v2
	s_waitcnt vmcnt(9)
	ds_write_b16 v2, v14 offset:17408
	ds_write_b16_d16_hi v2, v14 offset:17680
	ds_write_b16 v2, v15 offset:17952
	ds_write_b16_d16_hi v2, v15 offset:18224
	v_ashrrev_i32_e32 v2, 3, v30
	s_and_b64 vcc, s[28:29], exec
	s_mov_b32 s28, 0x80000380
	v_and_b32_e32 v2, -2, v2
	s_cselect_b32 s28, 0x80, s28
	v_add_u32_e32 v2, v23, v2
	v_cmp_eq_u32_e64 s[38:39], 0, v31
	s_and_b32 s28, s28, s3
	s_waitcnt vmcnt(7)
	v_lshlrev_b32_e32 v12, 16, v20
	v_and_b32_e32 v13, 0xffff0000, v20
	v_lshlrev_b32_e32 v15, 16, v21
	s_waitcnt vmcnt(6)
	v_lshlrev_b32_e32 v8, 16, v18
	v_and_b32_e32 v9, 0xffff0000, v18
	v_lshlrev_b32_e32 v14, 16, v19
	v_and_b32_e32 v11, 0xffff0000, v19
	v_and_b32_e32 v10, 0xffff0000, v21
	s_mov_b64 s[40:41], -1
	ds_write_b16 v2, v0 offset:17408
	ds_write_b16_d16_hi v2, v0 offset:17680
	ds_write_b16 v2, v1 offset:17952
	ds_write_b16_d16_hi v2, v1 offset:18224
	s_and_b64 vcc, exec, s[0:1]
	s_cbranch_vccz .Lkv_norot_b
	v_add_u32_e32 v32, s28, v40
	v_ashrrev_i32_e32 v32, 6, v32
	v_bfe_u32 v33, v38, 3, 6
	v_cndmask_b32_e64 v32, v33, v32, s[38:39]
	v_lshl_or_b32 v32, v32, 5, v200
	v_lshlrev_b32_e32 v50, 2, v32
	global_load_dwordx4 v[72:75], v50, s[12:13]
	global_load_dwordx4 v[76:79], v50, s[12:13] offset:16
	v_add_u32_e32 v32, s28, v42
	v_ashrrev_i32_e32 v32, 6, v32
	v_bfe_u32 v33, v54, 3, 6
	v_cndmask_b32_e64 v32, v33, v32, s[38:39]
	v_lshl_or_b32 v32, v32, 5, v200
	v_lshlrev_b32_e32 v51, 2, v32
	global_load_dwordx4 v[80:83], v51, s[12:13]
	global_load_dwordx4 v[84:87], v51, s[12:13] offset:16
	v_add_u32_e32 v32, s28, v43
	v_ashrrev_i32_e32 v32, 6, v32
	v_bfe_u32 v33, v55, 3, 6
	v_cndmask_b32_e64 v32, v33, v32, s[38:39]
	v_lshl_or_b32 v32, v32, 5, v200
	v_lshlrev_b32_e32 v52, 2, v32
	global_load_dwordx4 v[88:91], v52, s[12:13]
	global_load_dwordx4 v[92:95], v52, s[12:13] offset:16
	v_add_u32_e32 v32, s28, v44
	v_ashrrev_i32_e32 v32, 6, v32
	v_bfe_u32 v33, v56, 3, 6
	v_cndmask_b32_e64 v32, v33, v32, s[38:39]
	v_lshl_or_b32 v32, v32, 5, v200
	v_lshlrev_b32_e32 v53, 2, v32
	global_load_dwordx4 v[96:99], v53, s[12:13]
	global_load_dwordx4 v[100:103], v53, s[12:13] offset:16
	s_waitcnt vmcnt(0)
	v_mul_f32_e32 v34, v8, v73
	v_mul_f32_e32 v35, v12, v73
	v_fma_f32 v0, v12, v72, -v34
	v_fma_f32 v6, v8, v72, v35
	v_mul_f32_e32 v34, v9, v75
	v_mul_f32_e32 v35, v13, v75
	v_fma_f32 v1, v13, v74, -v34
	v_fma_f32 v7, v9, v74, v35
	v_mul_f32_e32 v34, v14, v77
	v_mul_f32_e32 v35, v15, v77
	v_fma_f32 v2, v15, v76, -v34
	v_fma_f32 v4, v14, v76, v35
	v_mul_f32_e32 v34, v11, v79
	v_mul_f32_e32 v35, v10, v79
	v_fma_f32 v3, v10, v78, -v34
	v_fma_f32 v5, v11, v78, v35
	v_lshlrev_b32_e32 v32, 16, v60
	v_lshlrev_b32_e32 v33, 16, v62
	v_mul_f32_e32 v34, v33, v81
	v_mul_f32_e32 v35, v32, v81
	v_fma_f32 v8, v32, v80, -v34
	v_fma_f32 v14, v33, v80, v35
	v_and_b32_e32 v32, 0xffff0000, v60
	v_and_b32_e32 v33, 0xffff0000, v62
	v_mul_f32_e32 v34, v33, v83
	v_mul_f32_e32 v35, v32, v83
	v_fma_f32 v9, v32, v82, -v34
	v_fma_f32 v15, v33, v82, v35
	v_lshlrev_b32_e32 v32, 16, v61
	v_lshlrev_b32_e32 v33, 16, v63
	v_mul_f32_e32 v34, v33, v85
	v_mul_f32_e32 v35, v32, v85
	v_fma_f32 v10, v32, v84, -v34
	v_fma_f32 v12, v33, v84, v35
	v_and_b32_e32 v32, 0xffff0000, v61
	v_and_b32_e32 v33, 0xffff0000, v63
	v_mul_f32_e32 v34, v33, v87
	v_mul_f32_e32 v35, v32, v87
	v_fma_f32 v11, v32, v86, -v34
	v_fma_f32 v13, v33, v86, v35
	v_lshlrev_b32_e32 v32, 16, v64
	v_lshlrev_b32_e32 v33, 16, v66
	v_mul_f32_e32 v34, v33, v89
	v_mul_f32_e32 v35, v32, v89
	v_fma_f32 v18, v32, v88, -v34
	v_fma_f32 v24, v33, v88, v35
	v_and_b32_e32 v32, 0xffff0000, v64
	v_and_b32_e32 v33, 0xffff0000, v66
	v_mul_f32_e32 v34, v33, v91
	v_mul_f32_e32 v35, v32, v91
	v_fma_f32 v19, v32, v90, -v34
	v_fma_f32 v25, v33, v90, v35
	v_lshlrev_b32_e32 v32, 16, v65
	v_lshlrev_b32_e32 v33, 16, v67
	v_mul_f32_e32 v34, v33, v93
	v_mul_f32_e32 v35, v32, v93
	v_fma_f32 v20, v32, v92, -v34
	v_fma_f32 v22, v33, v92, v35
	v_and_b32_e32 v32, 0xffff0000, v65
	v_and_b32_e32 v33, 0xffff0000, v67
	v_mul_f32_e32 v34, v33, v95
	v_mul_f32_e32 v35, v32, v95
	v_fma_f32 v21, v32, v94, -v34
	v_fma_f32 v23, v33, v94, v35
	v_lshlrev_b32_e32 v32, 16, v68
	v_lshlrev_b32_e32 v33, 16, v70
	v_mul_f32_e32 v34, v33, v97
	v_mul_f32_e32 v35, v32, v97
	v_fma_f32 v16, v32, v96, -v34
	v_fma_f32 v30, v33, v96, v35
	v_and_b32_e32 v32, 0xffff0000, v68
	v_and_b32_e32 v33, 0xffff0000, v70
	v_mul_f32_e32 v34, v33, v99
	v_mul_f32_e32 v35, v32, v99
	v_fma_f32 v17, v32, v98, -v34
	v_fma_f32 v31, v33, v98, v35
	v_lshlrev_b32_e32 v32, 16, v69
	v_lshlrev_b32_e32 v33, 16, v71
	v_mul_f32_e32 v34, v33, v101
	v_mul_f32_e32 v35, v32, v101
	v_fma_f32 v26, v32, v100, -v34
	v_fma_f32 v28, v33, v100, v35
	v_and_b32_e32 v32, 0xffff0000, v69
	v_and_b32_e32 v33, 0xffff0000, v71
	v_mul_f32_e32 v34, v33, v103
	v_mul_f32_e32 v35, v32, v103
	v_fma_f32 v27, v32, v102, -v34
	v_fma_f32 v29, v33, v102, v35
	s_branch .Lkv_done_b
